# attention: lazy lane-half exchange + PV block 1 ahead of the QK MFMAs and PV blocks 2,3 behind them (no PV/QK interleave) - chosen with a 4x-repeated-phase A/B amplifier
# speedup vs baseline: 1.0049x; 1.0006x over previous
.Lamla_loop:
	ds_read_b128 v[136:139], v243 offset:0
	ds_read_b128 v[140:143], v243 offset:6656
	ds_read_b128 v[144:147], v243 offset:32
	ds_read_b128 v[148:151], v243 offset:6688
	s_waitcnt lgkmcnt(10)
	v_mfma_f32_32x32x16_bf16 v[0:15], v[176:179], v[96:99], v[0:15]
	v_max3_f32 v168, v64, v65, v66
	v_max3_f32 v170, v80, v81, v82
	v_max3_f32 v168, v168, v67, v68
	v_max3_f32 v170, v170, v83, v84
	v_max3_f32 v168, v168, v69, v70
	s_mov_b32 s55, s52
	s_mov_b32 s52, s53
	s_mov_b32 s53, s54
	s_mov_b32 s54, s55
	s_mov_b32 s9, 0
	s_waitcnt lgkmcnt(8)
	v_mfma_f32_32x32x16_bf16 v[16:31], v[180:183], v[96:99], v[16:31]
	v_max3_f32 v170, v170, v85, v86
	v_max3_f32 v168, v168, v71, v72
	v_max3_f32 v170, v170, v87, v88
	v_max3_f32 v168, v168, v73, v74
	global_load_dwordx4 v[152:155], v167, s[2:3]
	global_load_dwordx2 v[160:161], v165, s[10:11]
	global_load_dwordx4 v[156:159], v167, s[4:5]
	s_add_u32 s2, s2, 0x2000
	s_addc_u32 s3, s3, 0
	s_add_u32 s10, s10, 0x1000
	s_addc_u32 s11, s11, 0
	s_add_u32 s4, s4, 0x2000
	s_addc_u32 s5, s5, 0
	v_add_u32_e32 v162, s53, v240
	v_add_u32_e32 v164, s54, v241
	v_mfma_f32_16x16x32_bf16 v[234:237], v[246:249], v[96:99], v[234:237]
	v_max3_f32 v170, v170, v89, v90
	v_max3_f32 v168, v168, v75, v76
	v_max3_f32 v170, v170, v91, v92
	v_max3_f32 v168, v168, v77, v78
	s_waitcnt lgkmcnt(6)
	v_mfma_f32_32x32x16_bf16 v[0:15], v[184:187], v[104:107], v[0:15]
	v_max3_f32 v170, v170, v93, v94
	v_max3_f32 v168, v168, v170, v79
	v_max_f32_e32 v168, v168, v95
	v_cmp_lt_f32_e32 vcc, 0x41000000, v168
	s_cbranch_vccz .Lamla_nors_2
	v_mov_b32_e32 v170, v168
	s_nop 1
	v_permlane32_swap_b32_e32 v168, v170
	v_max_f32_e32 v168, v168, v170
	v_max_f32_e32 v170, 0, v168
	v_exp_f32_e64 v166, -v170
	v_sub_f32_e32 v218, v218, v170
	v_sub_f32_e32 v219, v219, v170
	v_sub_f32_e32 v220, v220, v170
	v_sub_f32_e32 v221, v221, v170
	v_sub_f32_e32 v222, v222, v170
	v_sub_f32_e32 v223, v223, v170
	v_sub_f32_e32 v224, v224, v170
	v_sub_f32_e32 v225, v225, v170
	v_sub_f32_e32 v226, v226, v170
	v_sub_f32_e32 v227, v227, v170
	v_sub_f32_e32 v228, v228, v170
	v_sub_f32_e32 v229, v229, v170
	v_sub_f32_e32 v230, v230, v170
	v_sub_f32_e32 v231, v231, v170
	v_sub_f32_e32 v232, v232, v170
	v_sub_f32_e32 v233, v233, v170
	v_sub_f32_e32 v64, v64, v170
	v_sub_f32_e32 v65, v65, v170
	v_sub_f32_e32 v66, v66, v170
	v_sub_f32_e32 v67, v67, v170
	v_sub_f32_e32 v68, v68, v170
	v_sub_f32_e32 v69, v69, v170
	v_sub_f32_e32 v70, v70, v170
	v_sub_f32_e32 v71, v71, v170
	v_sub_f32_e32 v72, v72, v170
	v_sub_f32_e32 v73, v73, v170
	v_sub_f32_e32 v74, v74, v170
	v_sub_f32_e32 v75, v75, v170
	v_sub_f32_e32 v76, v76, v170
	v_sub_f32_e32 v77, v77, v170
	v_sub_f32_e32 v78, v78, v170
	v_sub_f32_e32 v79, v79, v170
	v_sub_f32_e32 v80, v80, v170
	v_sub_f32_e32 v81, v81, v170
	v_sub_f32_e32 v82, v82, v170
	v_sub_f32_e32 v83, v83, v170
	v_sub_f32_e32 v84, v84, v170
	v_sub_f32_e32 v85, v85, v170
	v_sub_f32_e32 v86, v86, v170
	v_sub_f32_e32 v87, v87, v170
	v_sub_f32_e32 v88, v88, v170
	v_sub_f32_e32 v89, v89, v170
	v_sub_f32_e32 v90, v90, v170
	v_sub_f32_e32 v91, v91, v170
	v_sub_f32_e32 v92, v92, v170
	v_sub_f32_e32 v93, v93, v170
	v_sub_f32_e32 v94, v94, v170
	v_sub_f32_e32 v95, v95, v170
	s_mov_b32 s9, 1
.Lamla_nors_2:
	ds_read_b64_tr_b16 v[192:193], v163 offset:3072
	ds_read_b64_tr_b16 v[194:195], v163 offset:4608
	s_waitcnt lgkmcnt(6)
	v_mfma_f32_32x32x16_bf16 v[16:31], v[188:191], v[104:107], v[16:31]
	v_exp_f32_e32 v64, v64
	v_exp_f32_e32 v80, v80
	ds_read_b64_tr_b16 v[196:197], v163 offset:3136
	ds_read_b64_tr_b16 v[198:199], v163 offset:4672
	v_mfma_f32_16x16x32_bf16 v[234:237], v[246:249], v[104:107], v[234:237]
	v_exp_f32_e32 v65, v65
	v_exp_f32_e32 v81, v81
	ds_read_b64_tr_b16 v[200:201], v163 offset:9216
	ds_read_b64_tr_b16 v[202:203], v163 offset:10752
	s_waitcnt lgkmcnt(9)
	v_mfma_f32_32x32x16_bf16 v[32:47], v[136:139], v[112:115], v[218:233]
	v_exp_f32_e32 v66, v66
	v_exp_f32_e32 v82, v82
	ds_read_b128 v[136:139], v243 offset:64
	ds_read_b64_tr_b16 v[204:205], v163 offset:9280
	ds_read_b64_tr_b16 v[206:207], v163 offset:10816
	s_waitcnt lgkmcnt(11)
	v_mfma_f32_32x32x16_bf16 v[48:63], v[140:143], v[112:115], v[218:233]
	v_cvt_pk_bf16_f32 v96, v64, v65
	v_cvt_pk_bf16_f32 v104, v80, v81
	v_exp_f32_e32 v67, v67
	ds_read_b128 v[140:143], v243 offset:6720
	s_waitcnt lgkmcnt(11)
	v_mfma_f32_32x32x16_bf16 v[32:47], v[144:147], v[116:119], v[32:47]
	v_exp_f32_e32 v83, v83
	v_exp_f32_e32 v68, v68
	ds_read_b128 v[144:147], v243 offset:96
	s_waitcnt lgkmcnt(11)
	v_mfma_f32_32x32x16_bf16 v[48:63], v[148:151], v[116:119], v[48:63]
	v_exp_f32_e32 v84, v84
	v_cvt_pk_bf16_f32 v97, v66, v67
	ds_read_b128 v[148:151], v243 offset:6752
	s_waitcnt lgkmcnt(5)
	v_mfma_f32_32x32x16_bf16 v[32:47], v[136:139], v[120:123], v[32:47]
	v_cvt_pk_bf16_f32 v105, v82, v83
	v_exp_f32_e32 v69, v69
	v_exp_f32_e32 v85, v85
	ds_read_b128 v[136:139], v243 offset:128
	s_waitcnt lgkmcnt(3)
	v_mfma_f32_32x32x16_bf16 v[48:63], v[140:143], v[120:123], v[48:63]
	v_exp_f32_e32 v70, v70
	v_exp_f32_e32 v86, v86
	ds_read_b128 v[140:143], v243 offset:6784
	s_waitcnt lgkmcnt(3)
	v_mfma_f32_32x32x16_bf16 v[32:47], v[144:147], v[124:127], v[32:47]
	v_cvt_pk_bf16_f32 v98, v68, v69
	v_cvt_pk_bf16_f32 v106, v84, v85
	v_exp_f32_e32 v71, v71
	ds_read_b128 v[144:147], v243 offset:160
	s_waitcnt lgkmcnt(3)
	v_mfma_f32_32x32x16_bf16 v[48:63], v[148:151], v[124:127], v[48:63]
	v_exp_f32_e32 v87, v87
	v_exp_f32_e32 v72, v72
	ds_read_b128 v[148:151], v243 offset:6816
	s_waitcnt lgkmcnt(3)
	v_mfma_f32_32x32x16_bf16 v[32:47], v[136:139], v[128:131], v[32:47]
	v_exp_f32_e32 v88, v88
	v_cvt_pk_bf16_f32 v99, v70, v71
	v_cvt_pk_bf16_f32 v107, v86, v87
	s_waitcnt vmcnt(5)
	ds_write_b128 v238, v[208:211] offset:13312
	s_waitcnt vmcnt(4)
	ds_write_b64 v239, v[216:217] offset:13312
	s_waitcnt vmcnt(3)
	ds_write_b128 v164, v[212:215]
	s_waitcnt lgkmcnt(5)
	v_mfma_f32_32x32x16_bf16 v[48:63], v[140:143], v[128:131], v[48:63]
	v_exp_f32_e32 v73, v73
	v_exp_f32_e32 v89, v89
	s_waitcnt lgkmcnt(4)
	v_mfma_f32_32x32x16_bf16 v[32:47], v[144:147], v[132:135], v[32:47]
	v_exp_f32_e32 v74, v74
	v_exp_f32_e32 v90, v90
	s_waitcnt lgkmcnt(3)
	v_mfma_f32_32x32x16_bf16 v[48:63], v[148:151], v[132:135], v[48:63]
	v_exp_f32_e32 v75, v75
	v_exp_f32_e32 v91, v91
	v_mfma_f32_32x32x16_bf16 v[0:15], v[192:195], v[100:103], v[0:15]
	v_exp_f32_e32 v76, v76
	v_exp_f32_e32 v92, v92
	ds_read_b64_tr_b16 v[176:177], v162 offset:0
	ds_read_b64_tr_b16 v[178:179], v162 offset:1536
	v_mfma_f32_32x32x16_bf16 v[16:31], v[196:199], v[100:103], v[16:31]
	v_exp_f32_e32 v77, v77
	v_exp_f32_e32 v93, v93
	ds_read_b64_tr_b16 v[180:181], v162 offset:64
	ds_read_b64_tr_b16 v[182:183], v162 offset:1600
	v_mfma_f32_16x16x32_bf16 v[234:237], v[246:249], v[100:103], v[234:237]
	v_cvt_pk_bf16_f32 v100, v72, v73
	v_cvt_pk_bf16_f32 v101, v74, v75
	v_exp_f32_e32 v78, v78
	v_exp_f32_e32 v94, v94
	ds_read_b64_tr_b16 v[184:185], v162 offset:6144
	ds_read_b64_tr_b16 v[186:187], v162 offset:7680
	v_mfma_f32_32x32x16_bf16 v[0:15], v[200:203], v[108:111], v[0:15]
	v_cvt_pk_bf16_f32 v102, v76, v77
	v_exp_f32_e32 v79, v79
	v_exp_f32_e32 v95, v95
	ds_read_b64_tr_b16 v[188:189], v162 offset:6208
	ds_read_b64_tr_b16 v[190:191], v162 offset:7744
	v_mfma_f32_32x32x16_bf16 v[16:31], v[204:207], v[108:111], v[16:31]
	v_cvt_pk_bf16_f32 v103, v78, v79
	v_mfma_f32_16x16x32_bf16 v[234:237], v[246:249], v[108:111], v[234:237]
	v_cvt_pk_bf16_f32 v108, v88, v89
	v_cvt_pk_bf16_f32 v109, v90, v91
	v_cvt_pk_bf16_f32 v110, v92, v93
	v_cvt_pk_bf16_f32 v111, v94, v95
	s_cmp_lg_u32 s9, 0
	s_cbranch_scc0 .Lamla_noresc_3
	s_nop 15
	v_mul_f32_e32 v0, v0, v166
	v_mul_f32_e32 v1, v1, v166
	v_mul_f32_e32 v2, v2, v166
	v_mul_f32_e32 v3, v3, v166
	v_mul_f32_e32 v4, v4, v166
	v_mul_f32_e32 v5, v5, v166
	v_mul_f32_e32 v6, v6, v166
	v_mul_f32_e32 v7, v7, v166
	v_mul_f32_e32 v8, v8, v166
	v_mul_f32_e32 v9, v9, v166
	v_mul_f32_e32 v10, v10, v166
	v_mul_f32_e32 v11, v11, v166
	v_mul_f32_e32 v12, v12, v166
	v_mul_f32_e32 v13, v13, v166
	v_mul_f32_e32 v14, v14, v166
	v_mul_f32_e32 v15, v15, v166
	v_mul_f32_e32 v16, v16, v166
	v_mul_f32_e32 v17, v17, v166
	v_mul_f32_e32 v18, v18, v166
	v_mul_f32_e32 v19, v19, v166
	v_mul_f32_e32 v20, v20, v166
	v_mul_f32_e32 v21, v21, v166
	v_mul_f32_e32 v22, v22, v166
	v_mul_f32_e32 v23, v23, v166
	v_mul_f32_e32 v24, v24, v166
	v_mul_f32_e32 v25, v25, v166
	v_mul_f32_e32 v26, v26, v166
	v_mul_f32_e32 v27, v27, v166
	v_mul_f32_e32 v28, v28, v166
	v_mul_f32_e32 v29, v29, v166
	v_mul_f32_e32 v30, v30, v166
	v_mul_f32_e32 v31, v31, v166
	v_add_u32_e32 v170, 64, v175
	ds_bpermute_b32 v173, v170, v166
	v_mul_f32_e32 v234, v234, v166
	s_waitcnt lgkmcnt(0)
	v_mul_f32_e32 v235, v235, v173
.Lamla_noresc_3:
	s_waitcnt lgkmcnt(8)
	s_barrier
	ds_read_b128 v[136:139], v243 offset:13312
	ds_read_b128 v[140:143], v243 offset:19968
	ds_read_b128 v[144:147], v243 offset:13344
	ds_read_b128 v[148:151], v243 offset:20000
	s_waitcnt lgkmcnt(10)
	v_mfma_f32_32x32x16_bf16 v[0:15], v[176:179], v[96:99], v[0:15]
	v_max3_f32 v168, v32, v33, v34
	v_max3_f32 v170, v48, v49, v50
	v_max3_f32 v168, v168, v35, v36
	v_max3_f32 v170, v170, v51, v52
	v_max3_f32 v168, v168, v37, v38
	s_mov_b32 s55, s52
	s_mov_b32 s52, s53
	s_mov_b32 s53, s54
	s_mov_b32 s54, s55
	s_mov_b32 s9, 0
	s_waitcnt lgkmcnt(8)
	v_mfma_f32_32x32x16_bf16 v[16:31], v[180:183], v[96:99], v[16:31]
	v_max3_f32 v170, v170, v53, v54
	v_max3_f32 v168, v168, v39, v40
	v_max3_f32 v170, v170, v55, v56
	v_max3_f32 v168, v168, v41, v42
	global_load_dwordx4 v[208:211], v167, s[2:3]
	global_load_dwordx2 v[216:217], v165, s[10:11]
	global_load_dwordx4 v[212:215], v167, s[4:5]
	s_add_u32 s2, s2, 0x2000
	s_addc_u32 s3, s3, 0
	s_add_u32 s10, s10, 0x1000
	s_addc_u32 s11, s11, 0
	s_add_u32 s4, s4, 0x2000
	s_addc_u32 s5, s5, 0
	v_add_u32_e32 v163, s53, v240
	v_add_u32_e32 v164, s54, v241
	v_mfma_f32_16x16x32_bf16 v[234:237], v[246:249], v[96:99], v[234:237]
	v_max3_f32 v170, v170, v57, v58
	v_max3_f32 v168, v168, v43, v44
	v_max3_f32 v170, v170, v59, v60
	v_max3_f32 v168, v168, v45, v46
	s_waitcnt lgkmcnt(6)
	v_mfma_f32_32x32x16_bf16 v[0:15], v[184:187], v[104:107], v[0:15]
	v_max3_f32 v170, v170, v61, v62
	v_max3_f32 v168, v168, v170, v47
	v_max_f32_e32 v168, v168, v63
	v_cmp_lt_f32_e32 vcc, 0x41000000, v168
	s_cbranch_vccz .Lamla_nors_4
	v_mov_b32_e32 v170, v168
	s_nop 1
	v_permlane32_swap_b32_e32 v168, v170
	v_max_f32_e32 v168, v168, v170
	v_max_f32_e32 v170, 0, v168
	v_exp_f32_e64 v166, -v170
	v_sub_f32_e32 v218, v218, v170
	v_sub_f32_e32 v219, v219, v170
	v_sub_f32_e32 v220, v220, v170
	v_sub_f32_e32 v221, v221, v170
	v_sub_f32_e32 v222, v222, v170
	v_sub_f32_e32 v223, v223, v170
	v_sub_f32_e32 v224, v224, v170
	v_sub_f32_e32 v225, v225, v170
	v_sub_f32_e32 v226, v226, v170
	v_sub_f32_e32 v227, v227, v170
	v_sub_f32_e32 v228, v228, v170
	v_sub_f32_e32 v229, v229, v170
	v_sub_f32_e32 v230, v230, v170
	v_sub_f32_e32 v231, v231, v170
	v_sub_f32_e32 v232, v232, v170
	v_sub_f32_e32 v233, v233, v170
	v_sub_f32_e32 v32, v32, v170
	v_sub_f32_e32 v33, v33, v170
	v_sub_f32_e32 v34, v34, v170
	v_sub_f32_e32 v35, v35, v170
	v_sub_f32_e32 v36, v36, v170
	v_sub_f32_e32 v37, v37, v170
	v_sub_f32_e32 v38, v38, v170
	v_sub_f32_e32 v39, v39, v170
	v_sub_f32_e32 v40, v40, v170
	v_sub_f32_e32 v41, v41, v170
	v_sub_f32_e32 v42, v42, v170
	v_sub_f32_e32 v43, v43, v170
	v_sub_f32_e32 v44, v44, v170
	v_sub_f32_e32 v45, v45, v170
	v_sub_f32_e32 v46, v46, v170
	v_sub_f32_e32 v47, v47, v170
	v_sub_f32_e32 v48, v48, v170
	v_sub_f32_e32 v49, v49, v170
	v_sub_f32_e32 v50, v50, v170
	v_sub_f32_e32 v51, v51, v170
	v_sub_f32_e32 v52, v52, v170
	v_sub_f32_e32 v53, v53, v170
	v_sub_f32_e32 v54, v54, v170
	v_sub_f32_e32 v55, v55, v170
	v_sub_f32_e32 v56, v56, v170
	v_sub_f32_e32 v57, v57, v170
	v_sub_f32_e32 v58, v58, v170
	v_sub_f32_e32 v59, v59, v170
	v_sub_f32_e32 v60, v60, v170
	v_sub_f32_e32 v61, v61, v170
	v_sub_f32_e32 v62, v62, v170
	v_sub_f32_e32 v63, v63, v170
	s_mov_b32 s9, 1
.Lamla_nors_4:
	ds_read_b64_tr_b16 v[192:193], v162 offset:3072
	ds_read_b64_tr_b16 v[194:195], v162 offset:4608
	s_waitcnt lgkmcnt(6)
	v_mfma_f32_32x32x16_bf16 v[16:31], v[188:191], v[104:107], v[16:31]
	v_exp_f32_e32 v32, v32
	v_exp_f32_e32 v48, v48
	ds_read_b64_tr_b16 v[196:197], v162 offset:3136
	ds_read_b64_tr_b16 v[198:199], v162 offset:4672
	v_mfma_f32_16x16x32_bf16 v[234:237], v[246:249], v[104:107], v[234:237]
	v_exp_f32_e32 v33, v33
	v_exp_f32_e32 v49, v49
	ds_read_b64_tr_b16 v[200:201], v162 offset:9216
	ds_read_b64_tr_b16 v[202:203], v162 offset:10752
	s_waitcnt lgkmcnt(9)
	v_mfma_f32_32x32x16_bf16 v[64:79], v[136:139], v[112:115], v[218:233]
	v_exp_f32_e32 v34, v34
	v_exp_f32_e32 v50, v50
	ds_read_b128 v[136:139], v243 offset:13376
	ds_read_b64_tr_b16 v[204:205], v162 offset:9280
	ds_read_b64_tr_b16 v[206:207], v162 offset:10816
	s_waitcnt lgkmcnt(11)
	v_mfma_f32_32x32x16_bf16 v[80:95], v[140:143], v[112:115], v[218:233]
	v_cvt_pk_bf16_f32 v96, v32, v33
	v_cvt_pk_bf16_f32 v104, v48, v49
	v_exp_f32_e32 v35, v35
	ds_read_b128 v[140:143], v243 offset:20032
	s_waitcnt lgkmcnt(11)
	v_mfma_f32_32x32x16_bf16 v[64:79], v[144:147], v[116:119], v[64:79]
	v_exp_f32_e32 v51, v51
	v_exp_f32_e32 v36, v36
	ds_read_b128 v[144:147], v243 offset:13408
	s_waitcnt lgkmcnt(11)
	v_mfma_f32_32x32x16_bf16 v[80:95], v[148:151], v[116:119], v[80:95]
	v_exp_f32_e32 v52, v52
	v_cvt_pk_bf16_f32 v97, v34, v35
	ds_read_b128 v[148:151], v243 offset:20064
	s_waitcnt lgkmcnt(5)
	v_mfma_f32_32x32x16_bf16 v[64:79], v[136:139], v[120:123], v[64:79]
	v_cvt_pk_bf16_f32 v105, v50, v51
	v_exp_f32_e32 v37, v37
	v_exp_f32_e32 v53, v53
	ds_read_b128 v[136:139], v243 offset:13440
	s_waitcnt lgkmcnt(3)
	v_mfma_f32_32x32x16_bf16 v[80:95], v[140:143], v[120:123], v[80:95]
	v_exp_f32_e32 v38, v38
	v_exp_f32_e32 v54, v54
	ds_read_b128 v[140:143], v243 offset:20096
	s_waitcnt lgkmcnt(3)
	v_mfma_f32_32x32x16_bf16 v[64:79], v[144:147], v[124:127], v[64:79]
	v_cvt_pk_bf16_f32 v98, v36, v37
	v_cvt_pk_bf16_f32 v106, v52, v53
	v_exp_f32_e32 v39, v39
	ds_read_b128 v[144:147], v243 offset:13472
	s_waitcnt lgkmcnt(3)
	v_mfma_f32_32x32x16_bf16 v[80:95], v[148:151], v[124:127], v[80:95]
	v_exp_f32_e32 v55, v55
	v_exp_f32_e32 v40, v40
	ds_read_b128 v[148:151], v243 offset:20128
	s_waitcnt lgkmcnt(3)
	v_mfma_f32_32x32x16_bf16 v[64:79], v[136:139], v[128:131], v[64:79]
	v_exp_f32_e32 v56, v56
	v_cvt_pk_bf16_f32 v99, v38, v39
	v_cvt_pk_bf16_f32 v107, v54, v55
	s_waitcnt vmcnt(5)
	ds_write_b128 v238, v[152:155]
	s_waitcnt vmcnt(4)
	ds_write_b64 v239, v[160:161]
	s_waitcnt vmcnt(3)
	ds_write_b128 v164, v[156:159]
	s_waitcnt lgkmcnt(5)
	v_mfma_f32_32x32x16_bf16 v[80:95], v[140:143], v[128:131], v[80:95]
	v_exp_f32_e32 v41, v41
	v_exp_f32_e32 v57, v57
	s_waitcnt lgkmcnt(4)
	v_mfma_f32_32x32x16_bf16 v[64:79], v[144:147], v[132:135], v[64:79]
	v_exp_f32_e32 v42, v42
	v_exp_f32_e32 v58, v58
	s_waitcnt lgkmcnt(3)
	v_mfma_f32_32x32x16_bf16 v[80:95], v[148:151], v[132:135], v[80:95]
	v_exp_f32_e32 v43, v43
	v_exp_f32_e32 v59, v59
	v_mfma_f32_32x32x16_bf16 v[0:15], v[192:195], v[100:103], v[0:15]
	v_exp_f32_e32 v44, v44
	v_exp_f32_e32 v60, v60
	ds_read_b64_tr_b16 v[176:177], v163 offset:0
	ds_read_b64_tr_b16 v[178:179], v163 offset:1536
	v_mfma_f32_32x32x16_bf16 v[16:31], v[196:199], v[100:103], v[16:31]
	v_exp_f32_e32 v45, v45
	v_exp_f32_e32 v61, v61
	ds_read_b64_tr_b16 v[180:181], v163 offset:64
	ds_read_b64_tr_b16 v[182:183], v163 offset:1600
	v_mfma_f32_16x16x32_bf16 v[234:237], v[246:249], v[100:103], v[234:237]
	v_cvt_pk_bf16_f32 v100, v40, v41
	v_cvt_pk_bf16_f32 v101, v42, v43
	v_exp_f32_e32 v46, v46
	v_exp_f32_e32 v62, v62
	ds_read_b64_tr_b16 v[184:185], v163 offset:6144
	ds_read_b64_tr_b16 v[186:187], v163 offset:7680
	v_mfma_f32_32x32x16_bf16 v[0:15], v[200:203], v[108:111], v[0:15]
	v_cvt_pk_bf16_f32 v102, v44, v45
	v_exp_f32_e32 v47, v47
	v_exp_f32_e32 v63, v63
	ds_read_b64_tr_b16 v[188:189], v163 offset:6208
	ds_read_b64_tr_b16 v[190:191], v163 offset:7744
	v_mfma_f32_32x32x16_bf16 v[16:31], v[204:207], v[108:111], v[16:31]
	v_cvt_pk_bf16_f32 v103, v46, v47
	v_mfma_f32_16x16x32_bf16 v[234:237], v[246:249], v[108:111], v[234:237]
	v_cvt_pk_bf16_f32 v108, v56, v57
	v_cvt_pk_bf16_f32 v109, v58, v59
	v_cvt_pk_bf16_f32 v110, v60, v61
	v_cvt_pk_bf16_f32 v111, v62, v63
	s_cmp_lg_u32 s9, 0
	s_cbranch_scc0 .Lamla_noresc_5
	s_nop 15
	v_mul_f32_e32 v0, v0, v166
	v_mul_f32_e32 v1, v1, v166
	v_mul_f32_e32 v2, v2, v166
	v_mul_f32_e32 v3, v3, v166
	v_mul_f32_e32 v4, v4, v166
	v_mul_f32_e32 v5, v5, v166
	v_mul_f32_e32 v6, v6, v166
	v_mul_f32_e32 v7, v7, v166
	v_mul_f32_e32 v8, v8, v166
	v_mul_f32_e32 v9, v9, v166
	v_mul_f32_e32 v10, v10, v166
	v_mul_f32_e32 v11, v11, v166
	v_mul_f32_e32 v12, v12, v166
	v_mul_f32_e32 v13, v13, v166
	v_mul_f32_e32 v14, v14, v166
	v_mul_f32_e32 v15, v15, v166
	v_mul_f32_e32 v16, v16, v166
	v_mul_f32_e32 v17, v17, v166
	v_mul_f32_e32 v18, v18, v166
	v_mul_f32_e32 v19, v19, v166
	v_mul_f32_e32 v20, v20, v166
	v_mul_f32_e32 v21, v21, v166
	v_mul_f32_e32 v22, v22, v166
	v_mul_f32_e32 v23, v23, v166
	v_mul_f32_e32 v24, v24, v166
	v_mul_f32_e32 v25, v25, v166
	v_mul_f32_e32 v26, v26, v166
	v_mul_f32_e32 v27, v27, v166
	v_mul_f32_e32 v28, v28, v166
	v_mul_f32_e32 v29, v29, v166
	v_mul_f32_e32 v30, v30, v166
	v_mul_f32_e32 v31, v31, v166
	v_add_u32_e32 v170, 64, v175
	ds_bpermute_b32 v173, v170, v166
	v_mul_f32_e32 v234, v234, v166
	s_waitcnt lgkmcnt(0)
	v_mul_f32_e32 v235, v235, v173

; #define AT_GLOADK(k0) do { kreg = *(const u32x4*)(Kb + (size_t)((k0) + (tid >> 3)) * 64 + (tid & 7) * 8); \
;             if (MLA) preg = *(const u32x2*)(Pb + (size_t)((k0) + (tid >> 3)) * 32 + (tid & 7) * 4); } while (0)
; #define AT_GLOADV(k0) do { vreg = *(const u32x4*)(Vb + (size_t)((k0) + (tid >> 3)) * 64 + (tid & 7) * 8); } while (0)
; #define AT_WRITEK(buf) do { *(LAS u32x4*)(lds + (buf) * KBUF + (tid >> 3) * KSTR + (tid & 7) * 16) = kreg; \
;             if (MLA) *(LAS u32x2*)(lds + (buf) * KBUF + (tid >> 3) * KSTR + 128 + (tid & 7) * 8) = preg; } while (0)
; #define AT_WRITEV(buf) do { *(LAS u32x4*)(lds + 2 * KBUF + (buf) * VBUF + (tid >> 3) * VSTR + (tid & 7) * 16) = vreg; } while (0)
; #define AT_STEP(SC0, SC1, SN0, SN1, t, DOK, DOV) do { \
;             if (DOK) AT_GLOADK(((t) + 2) * 64); \
;             if (DOV) { AT_GLOADV(((t) + 1) * 64); AT_QK(SN0, SN1, ((t) + 1) & 1); } \
;             AT_SMPV(SC0, SC1, (t) & 1); \
;             if (DOK) AT_WRITEK((t) & 1); \
;             if (DOV) AT_WRITEV(((t) + 1) & 1); \
;             __syncthreads(); } while (0)
; template <bool MLA>
; DI void attn_phase(const int TID, const int BID, LAS unsigned char* lds, const Params& p, bool need_ctx) {
;     ...
;         f32x16 o0, o1, sa0, sa1, sb0, sb1;
; #pragma unroll
;         for (int j = 0; j < 16; ++j) { o0[j] = 0.f; o1[j] = 0.f; }
;         float mrun = -1e30f, lsum = 0.f;
;         if (wid >= 4) __builtin_amdgcn_s_setprio(1);
;         const int ntile = nk >> 6;
;         AT_GLOADK(0); AT_GLOADV(0); AT_WRITEK(0); AT_WRITEV(0);
;         AT_GLOADK(64); AT_WRITEK(1);
;         __syncthreads();
;         AT_QK(sa0, sa1, 0);
;         __syncthreads();
;         int t = 0;
;         for (; t < ntile - 2; t += 2) {
;             AT_STEP(sa0, sa1, sb0, sb1, t, true, true);
;             AT_STEP(sb0, sb1, sa0, sa1, t + 1, true, true);
;         }
;         AT_STEP(sa0, sa1, sb0, sb1, t, false, true);
;         AT_STEP(sb0, sb1, sa0, sa1, t + 1, false, false);
.Lamla_tail:
	ds_read_b128 v[136:139], v243 offset:0
	ds_read_b128 v[140:143], v243 offset:6656
	ds_read_b128 v[144:147], v243 offset:32
	ds_read_b128 v[148:151], v243 offset:6688
	s_waitcnt lgkmcnt(10)
	v_mfma_f32_32x32x16_bf16 v[0:15], v[176:179], v[96:99], v[0:15]
	v_max3_f32 v168, v64, v65, v66
	v_max3_f32 v170, v80, v81, v82
	v_max3_f32 v168, v168, v67, v68
	v_max3_f32 v170, v170, v83, v84
	v_max3_f32 v168, v168, v69, v70
	s_mov_b32 s55, s52
	s_mov_b32 s52, s53
	s_mov_b32 s53, s54
	s_mov_b32 s54, s55
	s_mov_b32 s9, 0
	s_waitcnt lgkmcnt(8)
	v_mfma_f32_32x32x16_bf16 v[16:31], v[180:183], v[96:99], v[16:31]
	v_max3_f32 v170, v170, v85, v86
	v_max3_f32 v168, v168, v71, v72
	v_max3_f32 v170, v170, v87, v88
	v_max3_f32 v168, v168, v73, v74
	global_load_dwordx4 v[156:159], v167, s[4:5]
	s_add_u32 s4, s4, 0x2000
	s_addc_u32 s5, s5, 0
	v_add_u32_e32 v162, s53, v240
	v_add_u32_e32 v164, s54, v241
	v_mfma_f32_16x16x32_bf16 v[234:237], v[246:249], v[96:99], v[234:237]
	v_max3_f32 v170, v170, v89, v90
	v_max3_f32 v168, v168, v75, v76
	v_max3_f32 v170, v170, v91, v92
	v_max3_f32 v168, v168, v77, v78
	s_waitcnt lgkmcnt(6)
	v_mfma_f32_32x32x16_bf16 v[0:15], v[184:187], v[104:107], v[0:15]
	v_max3_f32 v170, v170, v93, v94
	v_max3_f32 v168, v168, v170, v79
	v_max_f32_e32 v168, v168, v95
	v_cmp_lt_f32_e32 vcc, 0x41000000, v168
	s_cbranch_vccz .Lamla_nors_6
	v_mov_b32_e32 v170, v168
	s_nop 1
	v_permlane32_swap_b32_e32 v168, v170
	v_max_f32_e32 v168, v168, v170
	v_max_f32_e32 v170, 0, v168
	v_exp_f32_e64 v166, -v170
	v_sub_f32_e32 v218, v218, v170
	v_sub_f32_e32 v219, v219, v170
	v_sub_f32_e32 v220, v220, v170
	v_sub_f32_e32 v221, v221, v170
	v_sub_f32_e32 v222, v222, v170
	v_sub_f32_e32 v223, v223, v170
	v_sub_f32_e32 v224, v224, v170
	v_sub_f32_e32 v225, v225, v170
	v_sub_f32_e32 v226, v226, v170
	v_sub_f32_e32 v227, v227, v170
	v_sub_f32_e32 v228, v228, v170
	v_sub_f32_e32 v229, v229, v170
	v_sub_f32_e32 v230, v230, v170
	v_sub_f32_e32 v231, v231, v170
	v_sub_f32_e32 v232, v232, v170
	v_sub_f32_e32 v233, v233, v170
	v_sub_f32_e32 v64, v64, v170
	v_sub_f32_e32 v65, v65, v170
	v_sub_f32_e32 v66, v66, v170
	v_sub_f32_e32 v67, v67, v170
	v_sub_f32_e32 v68, v68, v170
	v_sub_f32_e32 v69, v69, v170
	v_sub_f32_e32 v70, v70, v170
	v_sub_f32_e32 v71, v71, v170
	v_sub_f32_e32 v72, v72, v170
	v_sub_f32_e32 v73, v73, v170
	v_sub_f32_e32 v74, v74, v170
	v_sub_f32_e32 v75, v75, v170
	v_sub_f32_e32 v76, v76, v170
	v_sub_f32_e32 v77, v77, v170
	v_sub_f32_e32 v78, v78, v170
	v_sub_f32_e32 v79, v79, v170
	v_sub_f32_e32 v80, v80, v170
	v_sub_f32_e32 v81, v81, v170
	v_sub_f32_e32 v82, v82, v170
	v_sub_f32_e32 v83, v83, v170
	v_sub_f32_e32 v84, v84, v170
	v_sub_f32_e32 v85, v85, v170
	v_sub_f32_e32 v86, v86, v170
	v_sub_f32_e32 v87, v87, v170
	v_sub_f32_e32 v88, v88, v170
	v_sub_f32_e32 v89, v89, v170
	v_sub_f32_e32 v90, v90, v170
	v_sub_f32_e32 v91, v91, v170
	v_sub_f32_e32 v92, v92, v170
	v_sub_f32_e32 v93, v93, v170
	v_sub_f32_e32 v94, v94, v170
	v_sub_f32_e32 v95, v95, v170
	s_mov_b32 s9, 1
.Lamla_nors_6:
	ds_read_b64_tr_b16 v[192:193], v163 offset:3072
	ds_read_b64_tr_b16 v[194:195], v163 offset:4608
	s_waitcnt lgkmcnt(6)
	v_mfma_f32_32x32x16_bf16 v[16:31], v[188:191], v[104:107], v[16:31]
	v_exp_f32_e32 v64, v64
	v_exp_f32_e32 v80, v80
	ds_read_b64_tr_b16 v[196:197], v163 offset:3136
	ds_read_b64_tr_b16 v[198:199], v163 offset:4672
	v_mfma_f32_16x16x32_bf16 v[234:237], v[246:249], v[104:107], v[234:237]
	v_exp_f32_e32 v65, v65
	v_exp_f32_e32 v81, v81
	ds_read_b64_tr_b16 v[200:201], v163 offset:9216
	ds_read_b64_tr_b16 v[202:203], v163 offset:10752
	s_waitcnt lgkmcnt(9)
	v_mfma_f32_32x32x16_bf16 v[32:47], v[136:139], v[112:115], v[218:233]
	v_exp_f32_e32 v66, v66
	v_exp_f32_e32 v82, v82
	ds_read_b128 v[136:139], v243 offset:64
	ds_read_b64_tr_b16 v[204:205], v163 offset:9280
	ds_read_b64_tr_b16 v[206:207], v163 offset:10816
	s_waitcnt lgkmcnt(11)
	v_mfma_f32_32x32x16_bf16 v[48:63], v[140:143], v[112:115], v[218:233]
	v_cvt_pk_bf16_f32 v96, v64, v65
	v_cvt_pk_bf16_f32 v104, v80, v81
	v_exp_f32_e32 v67, v67
	ds_read_b128 v[140:143], v243 offset:6720
	s_waitcnt lgkmcnt(11)
	v_mfma_f32_32x32x16_bf16 v[32:47], v[144:147], v[116:119], v[32:47]
	v_exp_f32_e32 v83, v83
	v_exp_f32_e32 v68, v68
	ds_read_b128 v[144:147], v243 offset:96
	s_waitcnt lgkmcnt(11)
	v_mfma_f32_32x32x16_bf16 v[48:63], v[148:151], v[116:119], v[48:63]
	v_exp_f32_e32 v84, v84
	v_cvt_pk_bf16_f32 v97, v66, v67
	ds_read_b128 v[148:151], v243 offset:6752
	s_waitcnt lgkmcnt(5)
	v_mfma_f32_32x32x16_bf16 v[32:47], v[136:139], v[120:123], v[32:47]
	v_cvt_pk_bf16_f32 v105, v82, v83
	v_exp_f32_e32 v69, v69
	v_exp_f32_e32 v85, v85
	ds_read_b128 v[136:139], v243 offset:128
	s_waitcnt lgkmcnt(3)
	v_mfma_f32_32x32x16_bf16 v[48:63], v[140:143], v[120:123], v[48:63]
	v_exp_f32_e32 v70, v70
	v_exp_f32_e32 v86, v86
	ds_read_b128 v[140:143], v243 offset:6784
	s_waitcnt lgkmcnt(3)
	v_mfma_f32_32x32x16_bf16 v[32:47], v[144:147], v[124:127], v[32:47]
	v_cvt_pk_bf16_f32 v98, v68, v69
	v_cvt_pk_bf16_f32 v106, v84, v85
	v_exp_f32_e32 v71, v71
	ds_read_b128 v[144:147], v243 offset:160
	s_waitcnt lgkmcnt(3)
	v_mfma_f32_32x32x16_bf16 v[48:63], v[148:151], v[124:127], v[48:63]
	v_exp_f32_e32 v87, v87
	v_exp_f32_e32 v72, v72
	ds_read_b128 v[148:151], v243 offset:6816
	s_waitcnt lgkmcnt(3)
	v_mfma_f32_32x32x16_bf16 v[32:47], v[136:139], v[128:131], v[32:47]
	v_exp_f32_e32 v88, v88
	v_cvt_pk_bf16_f32 v99, v70, v71
	v_cvt_pk_bf16_f32 v107, v86, v87
	s_waitcnt vmcnt(3)
	ds_write_b128 v238, v[208:211] offset:13312
	s_waitcnt vmcnt(2)
	ds_write_b64 v239, v[216:217] offset:13312
	s_waitcnt vmcnt(1)
	ds_write_b128 v164, v[212:215]
	s_waitcnt lgkmcnt(5)
; #define AT_GLOADK(k0) do { kreg = *(const u32x4*)(Kb + (size_t)((k0) + (tid >> 3)) * 64 + (tid & 7) * 8); \
;             if (MLA) preg = *(const u32x2*)(Pb + (size_t)((k0) + (tid >> 3)) * 32 + (tid & 7) * 4); } while (0)
; #define AT_GLOADV(k0) do { vreg = *(const u32x4*)(Vb + (size_t)((k0) + (tid >> 3)) * 64 + (tid & 7) * 8); } while (0)
; #define AT_WRITEK(buf) do { *(LAS u32x4*)(lds + (buf) * KBUF + (tid >> 3) * KSTR + (tid & 7) * 16) = kreg; \
;             if (MLA) *(LAS u32x2*)(lds + (buf) * KBUF + (tid >> 3) * KSTR + 128 + (tid & 7) * 8) = preg; } while (0)
; #define AT_WRITEV(buf) do { *(LAS u32x4*)(lds + 2 * KBUF + (buf) * VBUF + (tid >> 3) * VSTR + (tid & 7) * 16) = vreg; } while (0)
; #define AT_STEP(SC0, SC1, SN0, SN1, t, DOK, DOV) do { \
;             if (DOK) AT_GLOADK(((t) + 2) * 64); \
;             if (DOV) { AT_GLOADV(((t) + 1) * 64); AT_QK(SN0, SN1, ((t) + 1) & 1); } \
;             AT_SMPV(SC0, SC1, (t) & 1); \
;             if (DOK) AT_WRITEK((t) & 1); \
;             if (DOV) AT_WRITEV(((t) + 1) & 1); \
;             __syncthreads(); } while (0)
; template <bool MLA>
; DI void attn_phase(const int TID, const int BID, LAS unsigned char* lds, const Params& p, bool need_ctx) {
;     ...
;         f32x16 o0, o1, sa0, sa1, sb0, sb1;
; #pragma unroll
;         for (int j = 0; j < 16; ++j) { o0[j] = 0.f; o1[j] = 0.f; }
;         float mrun = -1e30f, lsum = 0.f;
;         if (wid >= 4) __builtin_amdgcn_s_setprio(1);
;         const int ntile = nk >> 6;
;         AT_GLOADK(0); AT_GLOADV(0); AT_WRITEK(0); AT_WRITEV(0);
;         AT_GLOADK(64); AT_WRITEK(1);
;         __syncthreads();
;         AT_QK(sa0, sa1, 0);
;         __syncthreads();
;         int t = 0;
;         for (; t < ntile - 2; t += 2) {
;             AT_STEP(sa0, sa1, sb0, sb1, t, true, true);
;             AT_STEP(sb0, sb1, sa0, sa1, t + 1, true, true);
;         }
;         AT_STEP(sa0, sa1, sb0, sb1, t, false, true);
;         AT_STEP(sb0, sb1, sa0, sa1, t + 1, false, false);
	v_mfma_f32_32x32x16_bf16 v[48:63], v[140:143], v[128:131], v[48:63]
	v_exp_f32_e32 v73, v73
	v_exp_f32_e32 v89, v89
	s_waitcnt lgkmcnt(4)
	v_mfma_f32_32x32x16_bf16 v[32:47], v[144:147], v[132:135], v[32:47]
	v_exp_f32_e32 v74, v74
	v_exp_f32_e32 v90, v90
	s_waitcnt lgkmcnt(3)
	v_mfma_f32_32x32x16_bf16 v[48:63], v[148:151], v[132:135], v[48:63]
	v_exp_f32_e32 v75, v75
	v_exp_f32_e32 v91, v91
	v_mfma_f32_32x32x16_bf16 v[0:15], v[192:195], v[100:103], v[0:15]
	v_exp_f32_e32 v76, v76
	v_exp_f32_e32 v92, v92
	ds_read_b64_tr_b16 v[176:177], v162 offset:0
	ds_read_b64_tr_b16 v[178:179], v162 offset:1536
	v_mfma_f32_32x32x16_bf16 v[16:31], v[196:199], v[100:103], v[16:31]
	v_exp_f32_e32 v77, v77
	v_exp_f32_e32 v93, v93
	ds_read_b64_tr_b16 v[180:181], v162 offset:64
	ds_read_b64_tr_b16 v[182:183], v162 offset:1600
	v_mfma_f32_16x16x32_bf16 v[234:237], v[246:249], v[100:103], v[234:237]
	v_cvt_pk_bf16_f32 v100, v72, v73
	v_cvt_pk_bf16_f32 v101, v74, v75
	v_exp_f32_e32 v78, v78
	v_exp_f32_e32 v94, v94
	ds_read_b64_tr_b16 v[184:185], v162 offset:6144
	ds_read_b64_tr_b16 v[186:187], v162 offset:7680
	v_mfma_f32_32x32x16_bf16 v[0:15], v[200:203], v[108:111], v[0:15]
	v_cvt_pk_bf16_f32 v102, v76, v77
	v_exp_f32_e32 v79, v79
	v_exp_f32_e32 v95, v95
	ds_read_b64_tr_b16 v[188:189], v162 offset:6208
	ds_read_b64_tr_b16 v[190:191], v162 offset:7744
	v_mfma_f32_32x32x16_bf16 v[16:31], v[204:207], v[108:111], v[16:31]
	v_cvt_pk_bf16_f32 v103, v78, v79
	v_mfma_f32_16x16x32_bf16 v[234:237], v[246:249], v[108:111], v[234:237]
	v_cvt_pk_bf16_f32 v108, v88, v89
	v_cvt_pk_bf16_f32 v109, v90, v91
	v_cvt_pk_bf16_f32 v110, v92, v93
	v_cvt_pk_bf16_f32 v111, v94, v95
	s_cmp_lg_u32 s9, 0
	s_cbranch_scc0 .Lamla_noresc_7
	s_nop 15
	v_mul_f32_e32 v0, v0, v166
	v_mul_f32_e32 v1, v1, v166
	v_mul_f32_e32 v2, v2, v166
	v_mul_f32_e32 v3, v3, v166
	v_mul_f32_e32 v4, v4, v166
	v_mul_f32_e32 v5, v5, v166
	v_mul_f32_e32 v6, v6, v166
	v_mul_f32_e32 v7, v7, v166
	v_mul_f32_e32 v8, v8, v166
	v_mul_f32_e32 v9, v9, v166
	v_mul_f32_e32 v10, v10, v166
	v_mul_f32_e32 v11, v11, v166
	v_mul_f32_e32 v12, v12, v166
	v_mul_f32_e32 v13, v13, v166
	v_mul_f32_e32 v14, v14, v166
	v_mul_f32_e32 v15, v15, v166
	v_mul_f32_e32 v16, v16, v166
	v_mul_f32_e32 v17, v17, v166
	v_mul_f32_e32 v18, v18, v166
	v_mul_f32_e32 v19, v19, v166
	v_mul_f32_e32 v20, v20, v166
	v_mul_f32_e32 v21, v21, v166
	v_mul_f32_e32 v22, v22, v166
	v_mul_f32_e32 v23, v23, v166
	v_mul_f32_e32 v24, v24, v166
	v_mul_f32_e32 v25, v25, v166
	v_mul_f32_e32 v26, v26, v166
	v_mul_f32_e32 v27, v27, v166
	v_mul_f32_e32 v28, v28, v166
	v_mul_f32_e32 v29, v29, v166
	v_mul_f32_e32 v30, v30, v166
	v_mul_f32_e32 v31, v31, v166
	v_add_u32_e32 v170, 64, v175
	ds_bpermute_b32 v173, v170, v166
	v_mul_f32_e32 v234, v234, v166
	s_waitcnt lgkmcnt(0)
	v_mul_f32_e32 v235, v235, v173
.Lamla_noresc_7:
	s_waitcnt lgkmcnt(8)
	s_barrier
	ds_read_b128 v[136:139], v243 offset:13312
	ds_read_b128 v[140:143], v243 offset:19968
	ds_read_b128 v[144:147], v243 offset:13344
	ds_read_b128 v[148:151], v243 offset:20000
	s_waitcnt lgkmcnt(10)
	v_mfma_f32_32x32x16_bf16 v[0:15], v[176:179], v[96:99], v[0:15]
	v_max3_f32 v168, v32, v33, v34
	v_max3_f32 v170, v48, v49, v50
	v_max3_f32 v168, v168, v35, v36
	v_max3_f32 v170, v170, v51, v52
	v_max3_f32 v168, v168, v37, v38
	s_mov_b32 s55, s52
	s_mov_b32 s52, s53
	s_mov_b32 s53, s54
	s_mov_b32 s54, s55
	s_mov_b32 s9, 0
	s_waitcnt lgkmcnt(8)
	v_mfma_f32_32x32x16_bf16 v[16:31], v[180:183], v[96:99], v[16:31]
	v_max3_f32 v170, v170, v53, v54
	v_max3_f32 v168, v168, v39, v40
	v_max3_f32 v170, v170, v55, v56
	v_max3_f32 v168, v168, v41, v42
	v_add_u32_e32 v163, s53, v240
	v_add_u32_e32 v164, s54, v241
	v_mfma_f32_16x16x32_bf16 v[234:237], v[246:249], v[96:99], v[234:237]
	v_max3_f32 v170, v170, v57, v58
	v_max3_f32 v168, v168, v43, v44
	v_max3_f32 v170, v170, v59, v60
	v_max3_f32 v168, v168, v45, v46
	s_waitcnt lgkmcnt(6)
	v_mfma_f32_32x32x16_bf16 v[0:15], v[184:187], v[104:107], v[0:15]
	v_max3_f32 v170, v170, v61, v62
	v_max3_f32 v168, v168, v170, v47
	v_max_f32_e32 v168, v168, v63
	v_cmp_lt_f32_e32 vcc, 0x41000000, v168
	s_cbranch_vccz .Lamla_nors_8
	v_mov_b32_e32 v170, v168
	s_nop 1
	v_permlane32_swap_b32_e32 v168, v170
	v_max_f32_e32 v168, v168, v170
	v_max_f32_e32 v170, 0, v168
	v_exp_f32_e64 v166, -v170
	v_sub_f32_e32 v218, v218, v170
	v_sub_f32_e32 v219, v219, v170
	v_sub_f32_e32 v220, v220, v170
	v_sub_f32_e32 v221, v221, v170
	v_sub_f32_e32 v222, v222, v170
	v_sub_f32_e32 v223, v223, v170
	v_sub_f32_e32 v224, v224, v170
	v_sub_f32_e32 v225, v225, v170
	v_sub_f32_e32 v226, v226, v170
	v_sub_f32_e32 v227, v227, v170
	v_sub_f32_e32 v228, v228, v170
	v_sub_f32_e32 v229, v229, v170
	v_sub_f32_e32 v230, v230, v170
	v_sub_f32_e32 v231, v231, v170
	v_sub_f32_e32 v232, v232, v170
	v_sub_f32_e32 v233, v233, v170
	v_sub_f32_e32 v32, v32, v170
	v_sub_f32_e32 v33, v33, v170
	v_sub_f32_e32 v34, v34, v170
	v_sub_f32_e32 v35, v35, v170
	v_sub_f32_e32 v36, v36, v170
	v_sub_f32_e32 v37, v37, v170
	v_sub_f32_e32 v38, v38, v170
	v_sub_f32_e32 v39, v39, v170
	v_sub_f32_e32 v40, v40, v170
	v_sub_f32_e32 v41, v41, v170
	v_sub_f32_e32 v42, v42, v170
	v_sub_f32_e32 v43, v43, v170
	v_sub_f32_e32 v44, v44, v170
	v_sub_f32_e32 v45, v45, v170
	v_sub_f32_e32 v46, v46, v170
	v_sub_f32_e32 v47, v47, v170
	v_sub_f32_e32 v48, v48, v170
	v_sub_f32_e32 v49, v49, v170
	v_sub_f32_e32 v50, v50, v170
	v_sub_f32_e32 v51, v51, v170
	v_sub_f32_e32 v52, v52, v170
	v_sub_f32_e32 v53, v53, v170
	v_sub_f32_e32 v54, v54, v170
	v_sub_f32_e32 v55, v55, v170
	v_sub_f32_e32 v56, v56, v170
	v_sub_f32_e32 v57, v57, v170
	v_sub_f32_e32 v58, v58, v170
	v_sub_f32_e32 v59, v59, v170
	v_sub_f32_e32 v60, v60, v170
	v_sub_f32_e32 v61, v61, v170
	v_sub_f32_e32 v62, v62, v170
	v_sub_f32_e32 v63, v63, v170
	s_mov_b32 s9, 1
.Lamla_nors_8:
	ds_read_b64_tr_b16 v[192:193], v162 offset:3072
	ds_read_b64_tr_b16 v[194:195], v162 offset:4608
	s_waitcnt lgkmcnt(6)
	v_mfma_f32_32x32x16_bf16 v[16:31], v[188:191], v[104:107], v[16:31]
	v_exp_f32_e32 v32, v32
	v_exp_f32_e32 v48, v48
	ds_read_b64_tr_b16 v[196:197], v162 offset:3136
	ds_read_b64_tr_b16 v[198:199], v162 offset:4672
	v_mfma_f32_16x16x32_bf16 v[234:237], v[246:249], v[104:107], v[234:237]
	v_exp_f32_e32 v33, v33
	v_exp_f32_e32 v49, v49
	ds_read_b64_tr_b16 v[200:201], v162 offset:9216
	ds_read_b64_tr_b16 v[202:203], v162 offset:10752
	s_waitcnt lgkmcnt(9)
	v_mfma_f32_32x32x16_bf16 v[64:79], v[136:139], v[112:115], v[218:233]
	v_exp_f32_e32 v34, v34
	v_exp_f32_e32 v50, v50
	ds_read_b128 v[136:139], v243 offset:13376
	ds_read_b64_tr_b16 v[204:205], v162 offset:9280
	ds_read_b64_tr_b16 v[206:207], v162 offset:10816
	s_waitcnt lgkmcnt(11)
	v_mfma_f32_32x32x16_bf16 v[80:95], v[140:143], v[112:115], v[218:233]
	v_cvt_pk_bf16_f32 v96, v32, v33
	v_cvt_pk_bf16_f32 v104, v48, v49
	v_exp_f32_e32 v35, v35
	ds_read_b128 v[140:143], v243 offset:20032
	s_waitcnt lgkmcnt(11)
	v_mfma_f32_32x32x16_bf16 v[64:79], v[144:147], v[116:119], v[64:79]
	v_exp_f32_e32 v51, v51
	v_exp_f32_e32 v36, v36
	ds_read_b128 v[144:147], v243 offset:13408
	s_waitcnt lgkmcnt(11)
	v_mfma_f32_32x32x16_bf16 v[80:95], v[148:151], v[116:119], v[80:95]
	v_exp_f32_e32 v52, v52
	v_cvt_pk_bf16_f32 v97, v34, v35
	ds_read_b128 v[148:151], v243 offset:20064
	s_waitcnt lgkmcnt(5)
	v_mfma_f32_32x32x16_bf16 v[64:79], v[136:139], v[120:123], v[64:79]
	v_cvt_pk_bf16_f32 v105, v50, v51
	v_exp_f32_e32 v37, v37
	v_exp_f32_e32 v53, v53
	ds_read_b128 v[136:139], v243 offset:13440
	s_waitcnt lgkmcnt(3)
	v_mfma_f32_32x32x16_bf16 v[80:95], v[140:143], v[120:123], v[80:95]
	v_exp_f32_e32 v38, v38
	v_exp_f32_e32 v54, v54
	ds_read_b128 v[140:143], v243 offset:20096
	s_waitcnt lgkmcnt(3)
	v_mfma_f32_32x32x16_bf16 v[64:79], v[144:147], v[124:127], v[64:79]
	v_cvt_pk_bf16_f32 v98, v36, v37
	v_cvt_pk_bf16_f32 v106, v52, v53
	v_exp_f32_e32 v39, v39
	ds_read_b128 v[144:147], v243 offset:13472
	s_waitcnt lgkmcnt(3)
	v_mfma_f32_32x32x16_bf16 v[80:95], v[148:151], v[124:127], v[80:95]
	v_exp_f32_e32 v55, v55
	v_exp_f32_e32 v40, v40
	ds_read_b128 v[148:151], v243 offset:20128
	s_waitcnt lgkmcnt(3)
	v_mfma_f32_32x32x16_bf16 v[64:79], v[136:139], v[128:131], v[64:79]
	v_exp_f32_e32 v56, v56
	v_cvt_pk_bf16_f32 v99, v38, v39
	v_cvt_pk_bf16_f32 v107, v54, v55
	s_waitcnt vmcnt(0)
	ds_write_b128 v164, v[156:159]
	s_waitcnt lgkmcnt(3)
	v_mfma_f32_32x32x16_bf16 v[80:95], v[140:143], v[128:131], v[80:95]
	v_exp_f32_e32 v41, v41
	v_exp_f32_e32 v57, v57
	s_waitcnt lgkmcnt(2)
	v_mfma_f32_32x32x16_bf16 v[64:79], v[144:147], v[132:135], v[64:79]
	v_exp_f32_e32 v42, v42
	v_exp_f32_e32 v58, v58
	s_waitcnt lgkmcnt(1)
	v_mfma_f32_32x32x16_bf16 v[80:95], v[148:151], v[132:135], v[80:95]
	v_exp_f32_e32 v43, v43
	v_exp_f32_e32 v59, v59
	v_mfma_f32_32x32x16_bf16 v[0:15], v[192:195], v[100:103], v[0:15]
	v_exp_f32_e32 v44, v44
	v_exp_f32_e32 v60, v60
	ds_read_b64_tr_b16 v[176:177], v163 offset:0
	ds_read_b64_tr_b16 v[178:179], v163 offset:1536
	v_mfma_f32_32x32x16_bf16 v[16:31], v[196:199], v[100:103], v[16:31]
	v_exp_f32_e32 v45, v45
	v_exp_f32_e32 v61, v61
	ds_read_b64_tr_b16 v[180:181], v163 offset:64
	ds_read_b64_tr_b16 v[182:183], v163 offset:1600
	v_mfma_f32_16x16x32_bf16 v[234:237], v[246:249], v[100:103], v[234:237]
	v_cvt_pk_bf16_f32 v100, v40, v41
	v_cvt_pk_bf16_f32 v101, v42, v43
	v_exp_f32_e32 v46, v46
	v_exp_f32_e32 v62, v62
	ds_read_b64_tr_b16 v[184:185], v163 offset:6144
	ds_read_b64_tr_b16 v[186:187], v163 offset:7680
	v_mfma_f32_32x32x16_bf16 v[0:15], v[200:203], v[108:111], v[0:15]
	v_cvt_pk_bf16_f32 v102, v44, v45
	v_exp_f32_e32 v47, v47
	v_exp_f32_e32 v63, v63
	ds_read_b64_tr_b16 v[188:189], v163 offset:6208
	ds_read_b64_tr_b16 v[190:191], v163 offset:7744
	v_mfma_f32_32x32x16_bf16 v[16:31], v[204:207], v[108:111], v[16:31]
	v_cvt_pk_bf16_f32 v103, v46, v47
	v_mfma_f32_16x16x32_bf16 v[234:237], v[246:249], v[108:111], v[234:237]
	v_cvt_pk_bf16_f32 v108, v56, v57
	v_cvt_pk_bf16_f32 v109, v58, v59
	v_cvt_pk_bf16_f32 v110, v60, v61
	v_cvt_pk_bf16_f32 v111, v62, v63
	s_cmp_lg_u32 s9, 0
	s_cbranch_scc0 .Lamla_noresc_9
	s_nop 15
	v_mul_f32_e32 v0, v0, v166
	v_mul_f32_e32 v1, v1, v166
	v_mul_f32_e32 v2, v2, v166
	v_mul_f32_e32 v3, v3, v166
	v_mul_f32_e32 v4, v4, v166
	v_mul_f32_e32 v5, v5, v166
	v_mul_f32_e32 v6, v6, v166
	v_mul_f32_e32 v7, v7, v166
	v_mul_f32_e32 v8, v8, v166
	v_mul_f32_e32 v9, v9, v166
	v_mul_f32_e32 v10, v10, v166
	v_mul_f32_e32 v11, v11, v166
	v_mul_f32_e32 v12, v12, v166
	v_mul_f32_e32 v13, v13, v166
	v_mul_f32_e32 v14, v14, v166
	v_mul_f32_e32 v15, v15, v166
	v_mul_f32_e32 v16, v16, v166
	v_mul_f32_e32 v17, v17, v166
	v_mul_f32_e32 v18, v18, v166
	v_mul_f32_e32 v19, v19, v166
	v_mul_f32_e32 v20, v20, v166
	v_mul_f32_e32 v21, v21, v166
	v_mul_f32_e32 v22, v22, v166
	v_mul_f32_e32 v23, v23, v166
	v_mul_f32_e32 v24, v24, v166
	v_mul_f32_e32 v25, v25, v166
	v_mul_f32_e32 v26, v26, v166
	v_mul_f32_e32 v27, v27, v166
	v_mul_f32_e32 v28, v28, v166
	v_mul_f32_e32 v29, v29, v166
	v_mul_f32_e32 v30, v30, v166
	v_mul_f32_e32 v31, v31, v166
	v_add_u32_e32 v170, 64, v175
	ds_bpermute_b32 v173, v170, v166
	v_mul_f32_e32 v234, v234, v166
	s_waitcnt lgkmcnt(0)
	v_mul_f32_e32 v235, v235, v173

.Lagqa_loop:
	ds_read_b128 v[136:139], v243 offset:0
	ds_read_b128 v[140:143], v243 offset:4608
	ds_read_b128 v[144:147], v243 offset:32
	ds_read_b128 v[148:151], v243 offset:4640
	s_waitcnt lgkmcnt(10)
	v_mfma_f32_32x32x16_bf16 v[0:15], v[176:179], v[96:99], v[0:15]
	v_max3_f32 v168, v64, v65, v66
	v_max3_f32 v170, v80, v81, v82
	v_max3_f32 v168, v168, v67, v68
	v_max3_f32 v170, v170, v83, v84
	v_max3_f32 v168, v168, v69, v70
	s_mov_b32 s55, s52
	s_mov_b32 s52, s53
	s_mov_b32 s53, s54
	s_mov_b32 s54, s55
	s_mov_b32 s9, 0
	s_waitcnt lgkmcnt(8)
	v_mfma_f32_32x32x16_bf16 v[16:31], v[180:183], v[96:99], v[16:31]
	v_max3_f32 v170, v170, v85, v86
	v_max3_f32 v168, v168, v71, v72
	v_max3_f32 v170, v170, v87, v88
	v_max3_f32 v168, v168, v73, v74
	v_max3_f32 v170, v170, v89, v90
	global_load_dwordx4 v[152:155], v167, s[2:3]
	global_load_dwordx4 v[156:159], v167, s[4:5]
	s_add_u32 s2, s2, 0x2000
	s_addc_u32 s3, s3, 0
	s_add_u32 s4, s4, 0x2000
	s_addc_u32 s5, s5, 0
	v_add_u32_e32 v162, s53, v240
	v_add_u32_e32 v164, s54, v241
	v_mfma_f32_16x16x32_bf16 v[234:237], v[246:249], v[96:99], v[234:237]
	v_max3_f32 v168, v168, v75, v76
	v_max3_f32 v170, v170, v91, v92
	v_max3_f32 v168, v168, v77, v78
	v_max3_f32 v170, v170, v93, v94
	v_max3_f32 v168, v168, v170, v79
	s_waitcnt lgkmcnt(6)
	v_mfma_f32_32x32x16_bf16 v[0:15], v[184:187], v[104:107], v[0:15]
	v_max_f32_e32 v168, v168, v95
	v_cmp_lt_f32_e32 vcc, 0x41000000, v168
	s_cbranch_vccz .Lagqa_nors_2
	v_mov_b32_e32 v170, v168
	s_nop 1
	v_permlane32_swap_b32_e32 v168, v170
	v_max_f32_e32 v168, v168, v170
	v_max_f32_e32 v170, 0, v168
	v_exp_f32_e64 v166, -v170
	v_sub_f32_e32 v218, v218, v170
	v_sub_f32_e32 v219, v219, v170
	v_sub_f32_e32 v220, v220, v170
	v_sub_f32_e32 v221, v221, v170
	v_sub_f32_e32 v222, v222, v170
	v_sub_f32_e32 v223, v223, v170
	v_sub_f32_e32 v224, v224, v170
	v_sub_f32_e32 v225, v225, v170
	v_sub_f32_e32 v226, v226, v170
	v_sub_f32_e32 v227, v227, v170
	v_sub_f32_e32 v228, v228, v170
	v_sub_f32_e32 v229, v229, v170
	v_sub_f32_e32 v230, v230, v170
	v_sub_f32_e32 v231, v231, v170
	v_sub_f32_e32 v232, v232, v170
	v_sub_f32_e32 v233, v233, v170
	v_sub_f32_e32 v64, v64, v170
	v_sub_f32_e32 v65, v65, v170
	v_sub_f32_e32 v66, v66, v170
	v_sub_f32_e32 v67, v67, v170
	v_sub_f32_e32 v68, v68, v170
	v_sub_f32_e32 v69, v69, v170
	v_sub_f32_e32 v70, v70, v170
	v_sub_f32_e32 v71, v71, v170
	v_sub_f32_e32 v72, v72, v170
	v_sub_f32_e32 v73, v73, v170
	v_sub_f32_e32 v74, v74, v170
	v_sub_f32_e32 v75, v75, v170
	v_sub_f32_e32 v76, v76, v170
	v_sub_f32_e32 v77, v77, v170
	v_sub_f32_e32 v78, v78, v170
	v_sub_f32_e32 v79, v79, v170
	v_sub_f32_e32 v80, v80, v170
	v_sub_f32_e32 v81, v81, v170
	v_sub_f32_e32 v82, v82, v170
	v_sub_f32_e32 v83, v83, v170
	v_sub_f32_e32 v84, v84, v170
	v_sub_f32_e32 v85, v85, v170
	v_sub_f32_e32 v86, v86, v170
	v_sub_f32_e32 v87, v87, v170
	v_sub_f32_e32 v88, v88, v170
	v_sub_f32_e32 v89, v89, v170
	v_sub_f32_e32 v90, v90, v170
	v_sub_f32_e32 v91, v91, v170
	v_sub_f32_e32 v92, v92, v170
	v_sub_f32_e32 v93, v93, v170
	v_sub_f32_e32 v94, v94, v170
	v_sub_f32_e32 v95, v95, v170
	s_mov_b32 s9, 1
.Lagqa_nors_2:
	v_exp_f32_e32 v64, v64
	ds_read_b64_tr_b16 v[192:193], v163 offset:3072
	ds_read_b64_tr_b16 v[194:195], v163 offset:4608
	s_waitcnt lgkmcnt(6)
	v_mfma_f32_32x32x16_bf16 v[16:31], v[188:191], v[104:107], v[16:31]
	v_exp_f32_e32 v80, v80
	v_exp_f32_e32 v65, v65
	v_exp_f32_e32 v81, v81
	ds_read_b64_tr_b16 v[196:197], v163 offset:3136
	ds_read_b64_tr_b16 v[198:199], v163 offset:4672
	v_mfma_f32_16x16x32_bf16 v[234:237], v[246:249], v[104:107], v[234:237]
	v_exp_f32_e32 v66, v66
	v_exp_f32_e32 v82, v82
	ds_read_b64_tr_b16 v[200:201], v163 offset:9216
	ds_read_b64_tr_b16 v[202:203], v163 offset:10752
	s_waitcnt lgkmcnt(9)
	v_mfma_f32_32x32x16_bf16 v[32:47], v[136:139], v[112:115], v[218:233]
	v_cvt_pk_bf16_f32 v96, v64, v65
	v_cvt_pk_bf16_f32 v104, v80, v81
	v_exp_f32_e32 v67, v67
	v_exp_f32_e32 v83, v83
	ds_read_b128 v[136:139], v243 offset:64
	ds_read_b64_tr_b16 v[204:205], v163 offset:9280
	ds_read_b64_tr_b16 v[206:207], v163 offset:10816
	s_waitcnt lgkmcnt(11)
	v_mfma_f32_32x32x16_bf16 v[48:63], v[140:143], v[112:115], v[218:233]
	v_exp_f32_e32 v68, v68
	v_exp_f32_e32 v84, v84
	ds_read_b128 v[140:143], v243 offset:4672
	s_waitcnt lgkmcnt(11)
	v_mfma_f32_32x32x16_bf16 v[32:47], v[144:147], v[116:119], v[32:47]
	v_cvt_pk_bf16_f32 v97, v66, v67
	v_cvt_pk_bf16_f32 v105, v82, v83
	v_exp_f32_e32 v69, v69
	v_exp_f32_e32 v85, v85
	ds_read_b128 v[144:147], v243 offset:96
	s_waitcnt lgkmcnt(11)
	v_mfma_f32_32x32x16_bf16 v[48:63], v[148:151], v[116:119], v[48:63]
	v_exp_f32_e32 v70, v70
	v_exp_f32_e32 v86, v86
	ds_read_b128 v[148:151], v243 offset:4704
	s_waitcnt lgkmcnt(5)
	v_mfma_f32_32x32x16_bf16 v[32:47], v[136:139], v[120:123], v[32:47]
	v_cvt_pk_bf16_f32 v98, v68, v69
	v_cvt_pk_bf16_f32 v106, v84, v85
	v_exp_f32_e32 v71, v71
	s_waitcnt lgkmcnt(2)
	v_mfma_f32_32x32x16_bf16 v[48:63], v[140:143], v[120:123], v[48:63]
	v_exp_f32_e32 v87, v87
	v_exp_f32_e32 v72, v72
	v_exp_f32_e32 v88, v88
	s_waitcnt vmcnt(3)
	ds_write_b128 v238, v[208:211] offset:9216
	s_waitcnt vmcnt(2)
	ds_write_b128 v164, v[212:215]
	s_waitcnt lgkmcnt(3)
	v_mfma_f32_32x32x16_bf16 v[32:47], v[144:147], v[124:127], v[32:47]
	v_cvt_pk_bf16_f32 v99, v70, v71
	v_cvt_pk_bf16_f32 v107, v86, v87
	v_exp_f32_e32 v73, v73
	s_waitcnt lgkmcnt(2)
	v_mfma_f32_32x32x16_bf16 v[48:63], v[148:151], v[124:127], v[48:63]
	v_exp_f32_e32 v89, v89
	v_exp_f32_e32 v74, v74
	v_exp_f32_e32 v90, v90
	v_mfma_f32_32x32x16_bf16 v[0:15], v[192:195], v[100:103], v[0:15]
	v_exp_f32_e32 v75, v75
	v_exp_f32_e32 v91, v91
	ds_read_b64_tr_b16 v[176:177], v162 offset:0
	ds_read_b64_tr_b16 v[178:179], v162 offset:1536
	v_mfma_f32_32x32x16_bf16 v[16:31], v[196:199], v[100:103], v[16:31]
	v_exp_f32_e32 v76, v76
	v_exp_f32_e32 v92, v92
	v_exp_f32_e32 v77, v77
	ds_read_b64_tr_b16 v[180:181], v162 offset:64
	ds_read_b64_tr_b16 v[182:183], v162 offset:1600
	v_mfma_f32_16x16x32_bf16 v[234:237], v[246:249], v[100:103], v[234:237]
	v_cvt_pk_bf16_f32 v100, v72, v73
	v_cvt_pk_bf16_f32 v101, v74, v75
	v_exp_f32_e32 v93, v93
	v_exp_f32_e32 v78, v78
	ds_read_b64_tr_b16 v[184:185], v162 offset:6144
	ds_read_b64_tr_b16 v[186:187], v162 offset:7680
	v_mfma_f32_32x32x16_bf16 v[0:15], v[200:203], v[108:111], v[0:15]
	v_exp_f32_e32 v94, v94
	v_cvt_pk_bf16_f32 v102, v76, v77
	v_exp_f32_e32 v79, v79
	ds_read_b64_tr_b16 v[188:189], v162 offset:6208
	ds_read_b64_tr_b16 v[190:191], v162 offset:7744
	v_mfma_f32_32x32x16_bf16 v[16:31], v[204:207], v[108:111], v[16:31]
	v_exp_f32_e32 v95, v95
	v_cvt_pk_bf16_f32 v103, v78, v79
	v_mfma_f32_16x16x32_bf16 v[234:237], v[246:249], v[108:111], v[234:237]
	v_cvt_pk_bf16_f32 v108, v88, v89
	v_cvt_pk_bf16_f32 v109, v90, v91
	v_cvt_pk_bf16_f32 v110, v92, v93
	v_cvt_pk_bf16_f32 v111, v94, v95
	s_cmp_lg_u32 s9, 0
	s_cbranch_scc0 .Lagqa_noresc_3
	s_nop 15
	v_mul_f32_e32 v0, v0, v166
	v_mul_f32_e32 v1, v1, v166
	v_mul_f32_e32 v2, v2, v166
	v_mul_f32_e32 v3, v3, v166
	v_mul_f32_e32 v4, v4, v166
	v_mul_f32_e32 v5, v5, v166
	v_mul_f32_e32 v6, v6, v166
	v_mul_f32_e32 v7, v7, v166
	v_mul_f32_e32 v8, v8, v166
	v_mul_f32_e32 v9, v9, v166
	v_mul_f32_e32 v10, v10, v166
	v_mul_f32_e32 v11, v11, v166
	v_mul_f32_e32 v12, v12, v166
	v_mul_f32_e32 v13, v13, v166
	v_mul_f32_e32 v14, v14, v166
	v_mul_f32_e32 v15, v15, v166
	v_mul_f32_e32 v16, v16, v166
	v_mul_f32_e32 v17, v17, v166
	v_mul_f32_e32 v18, v18, v166
	v_mul_f32_e32 v19, v19, v166
	v_mul_f32_e32 v20, v20, v166
	v_mul_f32_e32 v21, v21, v166
	v_mul_f32_e32 v22, v22, v166
	v_mul_f32_e32 v23, v23, v166
	v_mul_f32_e32 v24, v24, v166
	v_mul_f32_e32 v25, v25, v166
	v_mul_f32_e32 v26, v26, v166
	v_mul_f32_e32 v27, v27, v166
	v_mul_f32_e32 v28, v28, v166
	v_mul_f32_e32 v29, v29, v166
	v_mul_f32_e32 v30, v30, v166
	v_mul_f32_e32 v31, v31, v166
	v_add_u32_e32 v170, 64, v175
	ds_bpermute_b32 v173, v170, v166
	v_mul_f32_e32 v234, v234, v166
	s_waitcnt lgkmcnt(0)
	v_mul_f32_e32 v235, v235, v173
.Lagqa_noresc_3:
	s_waitcnt lgkmcnt(8)
	s_barrier
	ds_read_b128 v[136:139], v243 offset:9216
	ds_read_b128 v[140:143], v243 offset:13824
	ds_read_b128 v[144:147], v243 offset:9248
	ds_read_b128 v[148:151], v243 offset:13856
	s_waitcnt lgkmcnt(10)
	v_mfma_f32_32x32x16_bf16 v[0:15], v[176:179], v[96:99], v[0:15]
	v_max3_f32 v168, v32, v33, v34
	v_max3_f32 v170, v48, v49, v50
	v_max3_f32 v168, v168, v35, v36
	v_max3_f32 v170, v170, v51, v52
	v_max3_f32 v168, v168, v37, v38
	s_mov_b32 s55, s52
	s_mov_b32 s52, s53
	s_mov_b32 s53, s54
	s_mov_b32 s54, s55
	s_mov_b32 s9, 0
	s_waitcnt lgkmcnt(8)
	v_mfma_f32_32x32x16_bf16 v[16:31], v[180:183], v[96:99], v[16:31]
	v_max3_f32 v170, v170, v53, v54
	v_max3_f32 v168, v168, v39, v40
	v_max3_f32 v170, v170, v55, v56
	v_max3_f32 v168, v168, v41, v42
	v_max3_f32 v170, v170, v57, v58
	global_load_dwordx4 v[208:211], v167, s[2:3]
	global_load_dwordx4 v[212:215], v167, s[4:5]
	s_add_u32 s2, s2, 0x2000
	s_addc_u32 s3, s3, 0
	s_add_u32 s4, s4, 0x2000
	s_addc_u32 s5, s5, 0
	v_add_u32_e32 v163, s53, v240
	v_add_u32_e32 v164, s54, v241
	v_mfma_f32_16x16x32_bf16 v[234:237], v[246:249], v[96:99], v[234:237]
	v_max3_f32 v168, v168, v43, v44
	v_max3_f32 v170, v170, v59, v60
	v_max3_f32 v168, v168, v45, v46
	v_max3_f32 v170, v170, v61, v62
	v_max3_f32 v168, v168, v170, v47
	s_waitcnt lgkmcnt(6)
	v_mfma_f32_32x32x16_bf16 v[0:15], v[184:187], v[104:107], v[0:15]
	v_max_f32_e32 v168, v168, v63
	v_cmp_lt_f32_e32 vcc, 0x41000000, v168
	s_cbranch_vccz .Lagqa_nors_4
	v_mov_b32_e32 v170, v168
	s_nop 1
	v_permlane32_swap_b32_e32 v168, v170
	v_max_f32_e32 v168, v168, v170
	v_max_f32_e32 v170, 0, v168
	v_exp_f32_e64 v166, -v170
	v_sub_f32_e32 v218, v218, v170
	v_sub_f32_e32 v219, v219, v170
	v_sub_f32_e32 v220, v220, v170
	v_sub_f32_e32 v221, v221, v170
	v_sub_f32_e32 v222, v222, v170
	v_sub_f32_e32 v223, v223, v170
	v_sub_f32_e32 v224, v224, v170
	v_sub_f32_e32 v225, v225, v170
	v_sub_f32_e32 v226, v226, v170
	v_sub_f32_e32 v227, v227, v170
	v_sub_f32_e32 v228, v228, v170
	v_sub_f32_e32 v229, v229, v170
	v_sub_f32_e32 v230, v230, v170
	v_sub_f32_e32 v231, v231, v170
	v_sub_f32_e32 v232, v232, v170
	v_sub_f32_e32 v233, v233, v170
	v_sub_f32_e32 v32, v32, v170
	v_sub_f32_e32 v33, v33, v170
	v_sub_f32_e32 v34, v34, v170
	v_sub_f32_e32 v35, v35, v170
	v_sub_f32_e32 v36, v36, v170
	v_sub_f32_e32 v37, v37, v170
	v_sub_f32_e32 v38, v38, v170
	v_sub_f32_e32 v39, v39, v170
	v_sub_f32_e32 v40, v40, v170
	v_sub_f32_e32 v41, v41, v170
	v_sub_f32_e32 v42, v42, v170
	v_sub_f32_e32 v43, v43, v170
	v_sub_f32_e32 v44, v44, v170
	v_sub_f32_e32 v45, v45, v170
	v_sub_f32_e32 v46, v46, v170
	v_sub_f32_e32 v47, v47, v170
	v_sub_f32_e32 v48, v48, v170
	v_sub_f32_e32 v49, v49, v170
	v_sub_f32_e32 v50, v50, v170
	v_sub_f32_e32 v51, v51, v170
	v_sub_f32_e32 v52, v52, v170
	v_sub_f32_e32 v53, v53, v170
	v_sub_f32_e32 v54, v54, v170
	v_sub_f32_e32 v55, v55, v170
	v_sub_f32_e32 v56, v56, v170
	v_sub_f32_e32 v57, v57, v170
	v_sub_f32_e32 v58, v58, v170
	v_sub_f32_e32 v59, v59, v170
	v_sub_f32_e32 v60, v60, v170
	v_sub_f32_e32 v61, v61, v170
	v_sub_f32_e32 v62, v62, v170
	v_sub_f32_e32 v63, v63, v170
	s_mov_b32 s9, 1
.Lagqa_nors_4:
	v_exp_f32_e32 v32, v32
	ds_read_b64_tr_b16 v[192:193], v162 offset:3072
	ds_read_b64_tr_b16 v[194:195], v162 offset:4608
	s_waitcnt lgkmcnt(6)
	v_mfma_f32_32x32x16_bf16 v[16:31], v[188:191], v[104:107], v[16:31]
	v_exp_f32_e32 v48, v48
	v_exp_f32_e32 v33, v33
	v_exp_f32_e32 v49, v49
	ds_read_b64_tr_b16 v[196:197], v162 offset:3136
	ds_read_b64_tr_b16 v[198:199], v162 offset:4672
	v_mfma_f32_16x16x32_bf16 v[234:237], v[246:249], v[104:107], v[234:237]
	v_exp_f32_e32 v34, v34
	v_exp_f32_e32 v50, v50
	ds_read_b64_tr_b16 v[200:201], v162 offset:9216
	ds_read_b64_tr_b16 v[202:203], v162 offset:10752
	s_waitcnt lgkmcnt(9)
	v_mfma_f32_32x32x16_bf16 v[64:79], v[136:139], v[112:115], v[218:233]
	v_cvt_pk_bf16_f32 v96, v32, v33
	v_cvt_pk_bf16_f32 v104, v48, v49
	v_exp_f32_e32 v35, v35
	v_exp_f32_e32 v51, v51
	ds_read_b128 v[136:139], v243 offset:9280
	ds_read_b64_tr_b16 v[204:205], v162 offset:9280
	ds_read_b64_tr_b16 v[206:207], v162 offset:10816
	s_waitcnt lgkmcnt(11)
	v_mfma_f32_32x32x16_bf16 v[80:95], v[140:143], v[112:115], v[218:233]
	v_exp_f32_e32 v36, v36
	v_exp_f32_e32 v52, v52
	ds_read_b128 v[140:143], v243 offset:13888
	s_waitcnt lgkmcnt(11)
	v_mfma_f32_32x32x16_bf16 v[64:79], v[144:147], v[116:119], v[64:79]
	v_cvt_pk_bf16_f32 v97, v34, v35
	v_cvt_pk_bf16_f32 v105, v50, v51
	v_exp_f32_e32 v37, v37
	v_exp_f32_e32 v53, v53
	ds_read_b128 v[144:147], v243 offset:9312
	s_waitcnt lgkmcnt(11)
	v_mfma_f32_32x32x16_bf16 v[80:95], v[148:151], v[116:119], v[80:95]
	v_exp_f32_e32 v38, v38
	v_exp_f32_e32 v54, v54
	ds_read_b128 v[148:151], v243 offset:13920
	s_waitcnt lgkmcnt(5)
	v_mfma_f32_32x32x16_bf16 v[64:79], v[136:139], v[120:123], v[64:79]
	v_cvt_pk_bf16_f32 v98, v36, v37
	v_cvt_pk_bf16_f32 v106, v52, v53
	v_exp_f32_e32 v39, v39
	s_waitcnt lgkmcnt(2)
	v_mfma_f32_32x32x16_bf16 v[80:95], v[140:143], v[120:123], v[80:95]
	v_exp_f32_e32 v55, v55
	v_exp_f32_e32 v40, v40
	v_exp_f32_e32 v56, v56
	s_waitcnt vmcnt(3)
	ds_write_b128 v238, v[152:155]
	s_waitcnt vmcnt(2)
	ds_write_b128 v164, v[156:159]
	s_waitcnt lgkmcnt(3)
	v_mfma_f32_32x32x16_bf16 v[64:79], v[144:147], v[124:127], v[64:79]
	v_cvt_pk_bf16_f32 v99, v38, v39
	v_cvt_pk_bf16_f32 v107, v54, v55
	v_exp_f32_e32 v41, v41
	s_waitcnt lgkmcnt(2)
	v_mfma_f32_32x32x16_bf16 v[80:95], v[148:151], v[124:127], v[80:95]
	v_exp_f32_e32 v57, v57
	v_exp_f32_e32 v42, v42
	v_exp_f32_e32 v58, v58
	v_mfma_f32_32x32x16_bf16 v[0:15], v[192:195], v[100:103], v[0:15]
	v_exp_f32_e32 v43, v43
	v_exp_f32_e32 v59, v59
	ds_read_b64_tr_b16 v[176:177], v163 offset:0
	ds_read_b64_tr_b16 v[178:179], v163 offset:1536
	v_mfma_f32_32x32x16_bf16 v[16:31], v[196:199], v[100:103], v[16:31]
	v_exp_f32_e32 v44, v44
	v_exp_f32_e32 v60, v60
	v_exp_f32_e32 v45, v45
	ds_read_b64_tr_b16 v[180:181], v163 offset:64
	ds_read_b64_tr_b16 v[182:183], v163 offset:1600
	v_mfma_f32_16x16x32_bf16 v[234:237], v[246:249], v[100:103], v[234:237]
	v_cvt_pk_bf16_f32 v100, v40, v41
	v_cvt_pk_bf16_f32 v101, v42, v43
	v_exp_f32_e32 v61, v61
	v_exp_f32_e32 v46, v46
	ds_read_b64_tr_b16 v[184:185], v163 offset:6144
	ds_read_b64_tr_b16 v[186:187], v163 offset:7680
	v_mfma_f32_32x32x16_bf16 v[0:15], v[200:203], v[108:111], v[0:15]
	v_exp_f32_e32 v62, v62
	v_cvt_pk_bf16_f32 v102, v44, v45
	v_exp_f32_e32 v47, v47
	ds_read_b64_tr_b16 v[188:189], v163 offset:6208
	ds_read_b64_tr_b16 v[190:191], v163 offset:7744
	v_mfma_f32_32x32x16_bf16 v[16:31], v[204:207], v[108:111], v[16:31]
	v_exp_f32_e32 v63, v63
	v_cvt_pk_bf16_f32 v103, v46, v47
	v_mfma_f32_16x16x32_bf16 v[234:237], v[246:249], v[108:111], v[234:237]
	v_cvt_pk_bf16_f32 v108, v56, v57
	v_cvt_pk_bf16_f32 v109, v58, v59
	v_cvt_pk_bf16_f32 v110, v60, v61
	v_cvt_pk_bf16_f32 v111, v62, v63
	s_cmp_lg_u32 s9, 0
	s_cbranch_scc0 .Lagqa_noresc_5
	s_nop 15
	v_mul_f32_e32 v0, v0, v166
	v_mul_f32_e32 v1, v1, v166
	v_mul_f32_e32 v2, v2, v166
	v_mul_f32_e32 v3, v3, v166
	v_mul_f32_e32 v4, v4, v166
	v_mul_f32_e32 v5, v5, v166
	v_mul_f32_e32 v6, v6, v166
	v_mul_f32_e32 v7, v7, v166
	v_mul_f32_e32 v8, v8, v166
	v_mul_f32_e32 v9, v9, v166
	v_mul_f32_e32 v10, v10, v166
	v_mul_f32_e32 v11, v11, v166
	v_mul_f32_e32 v12, v12, v166
	v_mul_f32_e32 v13, v13, v166
	v_mul_f32_e32 v14, v14, v166
	v_mul_f32_e32 v15, v15, v166
	v_mul_f32_e32 v16, v16, v166
	v_mul_f32_e32 v17, v17, v166
	v_mul_f32_e32 v18, v18, v166
	v_mul_f32_e32 v19, v19, v166
	v_mul_f32_e32 v20, v20, v166
	v_mul_f32_e32 v21, v21, v166
	v_mul_f32_e32 v22, v22, v166
	v_mul_f32_e32 v23, v23, v166
	v_mul_f32_e32 v24, v24, v166
	v_mul_f32_e32 v25, v25, v166
	v_mul_f32_e32 v26, v26, v166
	v_mul_f32_e32 v27, v27, v166
	v_mul_f32_e32 v28, v28, v166
	v_mul_f32_e32 v29, v29, v166
	v_mul_f32_e32 v30, v30, v166
	v_mul_f32_e32 v31, v31, v166
	v_add_u32_e32 v170, 64, v175
	ds_bpermute_b32 v173, v170, v166
	v_mul_f32_e32 v234, v234, v166
	s_waitcnt lgkmcnt(0)
	v_mul_f32_e32 v235, v235, v173

; #define AT_STEP(SC0, SC1, SN0, SN1, t, DOK, DOV) do { \
;             if (DOK) AT_GLOADK(((t) + 2) * 64); \
;             if (DOV) { AT_GLOADV(((t) + 1) * 64); AT_QK(SN0, SN1, ((t) + 1) & 1); } \
;             AT_SMPV(SC0, SC1, (t) & 1); \
;             if (DOK) AT_WRITEK((t) & 1); \
;             if (DOV) AT_WRITEV(((t) + 1) & 1); \
;             __syncthreads(); } while (0)
; template <bool MLA>
; DI void attn_phase(const int TID, const int BID, LAS unsigned char* lds, const Params& p, bool need_ctx) {
;     ...
;         AT_STEP(sa0, sa1, sb0, sb1, t, false, true);
;         AT_STEP(sb0, sb1, sa0, sa1, t + 1, false, false);
.Lagqa_tail:
	ds_read_b128 v[136:139], v243 offset:0
	ds_read_b128 v[140:143], v243 offset:4608
	ds_read_b128 v[144:147], v243 offset:32
	ds_read_b128 v[148:151], v243 offset:4640
	s_waitcnt lgkmcnt(10)
	v_mfma_f32_32x32x16_bf16 v[0:15], v[176:179], v[96:99], v[0:15]
	v_max3_f32 v168, v64, v65, v66
	v_max3_f32 v170, v80, v81, v82
	v_max3_f32 v168, v168, v67, v68
	v_max3_f32 v170, v170, v83, v84
	v_max3_f32 v168, v168, v69, v70
	s_mov_b32 s55, s52
	s_mov_b32 s52, s53
	s_mov_b32 s53, s54
	s_mov_b32 s54, s55
	s_mov_b32 s9, 0
	s_waitcnt lgkmcnt(8)
	v_mfma_f32_32x32x16_bf16 v[16:31], v[180:183], v[96:99], v[16:31]
	v_max3_f32 v170, v170, v85, v86
	v_max3_f32 v168, v168, v71, v72
	v_max3_f32 v170, v170, v87, v88
	v_max3_f32 v168, v168, v73, v74
	v_max3_f32 v170, v170, v89, v90
	global_load_dwordx4 v[156:159], v167, s[4:5]
	s_add_u32 s4, s4, 0x2000
	s_addc_u32 s5, s5, 0
	v_add_u32_e32 v162, s53, v240
	v_add_u32_e32 v164, s54, v241
	v_mfma_f32_16x16x32_bf16 v[234:237], v[246:249], v[96:99], v[234:237]
	v_max3_f32 v168, v168, v75, v76
	v_max3_f32 v170, v170, v91, v92
	v_max3_f32 v168, v168, v77, v78
	v_max3_f32 v170, v170, v93, v94
	v_max3_f32 v168, v168, v170, v79
	s_waitcnt lgkmcnt(6)
	v_mfma_f32_32x32x16_bf16 v[0:15], v[184:187], v[104:107], v[0:15]
	v_max_f32_e32 v168, v168, v95
	v_cmp_lt_f32_e32 vcc, 0x41000000, v168
	s_cbranch_vccz .Lagqa_nors_6
	v_mov_b32_e32 v170, v168
	s_nop 1
	v_permlane32_swap_b32_e32 v168, v170
	v_max_f32_e32 v168, v168, v170
	v_max_f32_e32 v170, 0, v168
	v_exp_f32_e64 v166, -v170
	v_sub_f32_e32 v218, v218, v170
	v_sub_f32_e32 v219, v219, v170
	v_sub_f32_e32 v220, v220, v170
	v_sub_f32_e32 v221, v221, v170
	v_sub_f32_e32 v222, v222, v170
	v_sub_f32_e32 v223, v223, v170
	v_sub_f32_e32 v224, v224, v170
	v_sub_f32_e32 v225, v225, v170
	v_sub_f32_e32 v226, v226, v170
	v_sub_f32_e32 v227, v227, v170
	v_sub_f32_e32 v228, v228, v170
	v_sub_f32_e32 v229, v229, v170
	v_sub_f32_e32 v230, v230, v170
	v_sub_f32_e32 v231, v231, v170
	v_sub_f32_e32 v232, v232, v170
	v_sub_f32_e32 v233, v233, v170
	v_sub_f32_e32 v64, v64, v170
	v_sub_f32_e32 v65, v65, v170
	v_sub_f32_e32 v66, v66, v170
	v_sub_f32_e32 v67, v67, v170
	v_sub_f32_e32 v68, v68, v170
	v_sub_f32_e32 v69, v69, v170
	v_sub_f32_e32 v70, v70, v170
	v_sub_f32_e32 v71, v71, v170
	v_sub_f32_e32 v72, v72, v170
	v_sub_f32_e32 v73, v73, v170
	v_sub_f32_e32 v74, v74, v170
	v_sub_f32_e32 v75, v75, v170
	v_sub_f32_e32 v76, v76, v170
	v_sub_f32_e32 v77, v77, v170
	v_sub_f32_e32 v78, v78, v170
	v_sub_f32_e32 v79, v79, v170
	v_sub_f32_e32 v80, v80, v170
	v_sub_f32_e32 v81, v81, v170
	v_sub_f32_e32 v82, v82, v170
	v_sub_f32_e32 v83, v83, v170
	v_sub_f32_e32 v84, v84, v170
	v_sub_f32_e32 v85, v85, v170
	v_sub_f32_e32 v86, v86, v170
	v_sub_f32_e32 v87, v87, v170
	v_sub_f32_e32 v88, v88, v170
	v_sub_f32_e32 v89, v89, v170
	v_sub_f32_e32 v90, v90, v170
	v_sub_f32_e32 v91, v91, v170
	v_sub_f32_e32 v92, v92, v170
	v_sub_f32_e32 v93, v93, v170
	v_sub_f32_e32 v94, v94, v170
	v_sub_f32_e32 v95, v95, v170
	s_mov_b32 s9, 1
.Lagqa_nors_6:
	v_exp_f32_e32 v64, v64
	ds_read_b64_tr_b16 v[192:193], v163 offset:3072
	ds_read_b64_tr_b16 v[194:195], v163 offset:4608
	s_waitcnt lgkmcnt(6)
	v_mfma_f32_32x32x16_bf16 v[16:31], v[188:191], v[104:107], v[16:31]
	v_exp_f32_e32 v80, v80
	v_exp_f32_e32 v65, v65
	v_exp_f32_e32 v81, v81
	ds_read_b64_tr_b16 v[196:197], v163 offset:3136
	ds_read_b64_tr_b16 v[198:199], v163 offset:4672
	v_mfma_f32_16x16x32_bf16 v[234:237], v[246:249], v[104:107], v[234:237]
	v_exp_f32_e32 v66, v66
	v_exp_f32_e32 v82, v82
	ds_read_b64_tr_b16 v[200:201], v163 offset:9216
	ds_read_b64_tr_b16 v[202:203], v163 offset:10752
	s_waitcnt lgkmcnt(9)
	v_mfma_f32_32x32x16_bf16 v[32:47], v[136:139], v[112:115], v[218:233]
	v_cvt_pk_bf16_f32 v96, v64, v65
	v_cvt_pk_bf16_f32 v104, v80, v81
	v_exp_f32_e32 v67, v67
	v_exp_f32_e32 v83, v83
	ds_read_b128 v[136:139], v243 offset:64
	ds_read_b64_tr_b16 v[204:205], v163 offset:9280
	ds_read_b64_tr_b16 v[206:207], v163 offset:10816
	s_waitcnt lgkmcnt(11)
	v_mfma_f32_32x32x16_bf16 v[48:63], v[140:143], v[112:115], v[218:233]
	v_exp_f32_e32 v68, v68
	v_exp_f32_e32 v84, v84
	ds_read_b128 v[140:143], v243 offset:4672
	s_waitcnt lgkmcnt(11)
	v_mfma_f32_32x32x16_bf16 v[32:47], v[144:147], v[116:119], v[32:47]
	v_cvt_pk_bf16_f32 v97, v66, v67
	v_cvt_pk_bf16_f32 v105, v82, v83
	v_exp_f32_e32 v69, v69
	v_exp_f32_e32 v85, v85
	ds_read_b128 v[144:147], v243 offset:96
	s_waitcnt lgkmcnt(11)
	v_mfma_f32_32x32x16_bf16 v[48:63], v[148:151], v[116:119], v[48:63]
	v_exp_f32_e32 v70, v70
	v_exp_f32_e32 v86, v86
	ds_read_b128 v[148:151], v243 offset:4704
	s_waitcnt lgkmcnt(5)
	v_mfma_f32_32x32x16_bf16 v[32:47], v[136:139], v[120:123], v[32:47]
	v_cvt_pk_bf16_f32 v98, v68, v69
	v_cvt_pk_bf16_f32 v106, v84, v85
	v_exp_f32_e32 v71, v71
	s_waitcnt lgkmcnt(2)
	v_mfma_f32_32x32x16_bf16 v[48:63], v[140:143], v[120:123], v[48:63]
	v_exp_f32_e32 v87, v87
	v_exp_f32_e32 v72, v72
	v_exp_f32_e32 v88, v88
	s_waitcnt vmcnt(2)
	ds_write_b128 v238, v[208:211] offset:9216
	s_waitcnt vmcnt(1)
	ds_write_b128 v164, v[212:215]
	s_waitcnt lgkmcnt(3)
	v_mfma_f32_32x32x16_bf16 v[32:47], v[144:147], v[124:127], v[32:47]
	v_cvt_pk_bf16_f32 v99, v70, v71
	v_cvt_pk_bf16_f32 v107, v86, v87
	v_exp_f32_e32 v73, v73
	s_waitcnt lgkmcnt(2)
	v_mfma_f32_32x32x16_bf16 v[48:63], v[148:151], v[124:127], v[48:63]
	v_exp_f32_e32 v89, v89
	v_exp_f32_e32 v74, v74
	v_exp_f32_e32 v90, v90
	v_mfma_f32_32x32x16_bf16 v[0:15], v[192:195], v[100:103], v[0:15]
	v_exp_f32_e32 v75, v75
	v_exp_f32_e32 v91, v91
	ds_read_b64_tr_b16 v[176:177], v162 offset:0
	ds_read_b64_tr_b16 v[178:179], v162 offset:1536
	v_mfma_f32_32x32x16_bf16 v[16:31], v[196:199], v[100:103], v[16:31]
	v_exp_f32_e32 v76, v76
	v_exp_f32_e32 v92, v92
	v_exp_f32_e32 v77, v77
	ds_read_b64_tr_b16 v[180:181], v162 offset:64
	ds_read_b64_tr_b16 v[182:183], v162 offset:1600
	v_mfma_f32_16x16x32_bf16 v[234:237], v[246:249], v[100:103], v[234:237]
	v_cvt_pk_bf16_f32 v100, v72, v73
	v_cvt_pk_bf16_f32 v101, v74, v75
	v_exp_f32_e32 v93, v93
	v_exp_f32_e32 v78, v78
	ds_read_b64_tr_b16 v[184:185], v162 offset:6144
	ds_read_b64_tr_b16 v[186:187], v162 offset:7680
	v_mfma_f32_32x32x16_bf16 v[0:15], v[200:203], v[108:111], v[0:15]
	v_exp_f32_e32 v94, v94
	v_cvt_pk_bf16_f32 v102, v76, v77
	v_exp_f32_e32 v79, v79
	ds_read_b64_tr_b16 v[188:189], v162 offset:6208
	ds_read_b64_tr_b16 v[190:191], v162 offset:7744
	v_mfma_f32_32x32x16_bf16 v[16:31], v[204:207], v[108:111], v[16:31]
	v_exp_f32_e32 v95, v95
	v_cvt_pk_bf16_f32 v103, v78, v79
	v_mfma_f32_16x16x32_bf16 v[234:237], v[246:249], v[108:111], v[234:237]
	v_cvt_pk_bf16_f32 v108, v88, v89
	v_cvt_pk_bf16_f32 v109, v90, v91
	v_cvt_pk_bf16_f32 v110, v92, v93
	v_cvt_pk_bf16_f32 v111, v94, v95
	s_cmp_lg_u32 s9, 0
	s_cbranch_scc0 .Lagqa_noresc_7
; #define AT_STEP(SC0, SC1, SN0, SN1, t, DOK, DOV) do { \
;             if (DOK) AT_GLOADK(((t) + 2) * 64); \
;             if (DOV) { AT_GLOADV(((t) + 1) * 64); AT_QK(SN0, SN1, ((t) + 1) & 1); } \
;             AT_SMPV(SC0, SC1, (t) & 1); \
;             if (DOK) AT_WRITEK((t) & 1); \
;             if (DOV) AT_WRITEV(((t) + 1) & 1); \
;             __syncthreads(); } while (0)
; template <bool MLA>
; DI void attn_phase(const int TID, const int BID, LAS unsigned char* lds, const Params& p, bool need_ctx) {
;     ...
;         AT_STEP(sa0, sa1, sb0, sb1, t, false, true);
;         AT_STEP(sb0, sb1, sa0, sa1, t + 1, false, false);
	s_nop 15
	v_mul_f32_e32 v0, v0, v166
	v_mul_f32_e32 v1, v1, v166
	v_mul_f32_e32 v2, v2, v166
	v_mul_f32_e32 v3, v3, v166
	v_mul_f32_e32 v4, v4, v166
	v_mul_f32_e32 v5, v5, v166
	v_mul_f32_e32 v6, v6, v166
	v_mul_f32_e32 v7, v7, v166
	v_mul_f32_e32 v8, v8, v166
	v_mul_f32_e32 v9, v9, v166
	v_mul_f32_e32 v10, v10, v166
	v_mul_f32_e32 v11, v11, v166
	v_mul_f32_e32 v12, v12, v166
	v_mul_f32_e32 v13, v13, v166
	v_mul_f32_e32 v14, v14, v166
	v_mul_f32_e32 v15, v15, v166
	v_mul_f32_e32 v16, v16, v166
	v_mul_f32_e32 v17, v17, v166
	v_mul_f32_e32 v18, v18, v166
	v_mul_f32_e32 v19, v19, v166
	v_mul_f32_e32 v20, v20, v166
	v_mul_f32_e32 v21, v21, v166
	v_mul_f32_e32 v22, v22, v166
	v_mul_f32_e32 v23, v23, v166
	v_mul_f32_e32 v24, v24, v166
	v_mul_f32_e32 v25, v25, v166
	v_mul_f32_e32 v26, v26, v166
	v_mul_f32_e32 v27, v27, v166
	v_mul_f32_e32 v28, v28, v166
	v_mul_f32_e32 v29, v29, v166
	v_mul_f32_e32 v30, v30, v166
	v_mul_f32_e32 v31, v31, v166
	v_add_u32_e32 v170, 64, v175
	ds_bpermute_b32 v173, v170, v166
	v_mul_f32_e32 v234, v234, v166
	s_waitcnt lgkmcnt(0)
	v_mul_f32_e32 v235, v235, v173
.Lagqa_noresc_7:
	s_waitcnt lgkmcnt(8)
	s_barrier
	ds_read_b128 v[136:139], v243 offset:9216
	ds_read_b128 v[140:143], v243 offset:13824
	ds_read_b128 v[144:147], v243 offset:9248
	ds_read_b128 v[148:151], v243 offset:13856
	s_waitcnt lgkmcnt(10)
	v_mfma_f32_32x32x16_bf16 v[0:15], v[176:179], v[96:99], v[0:15]
	v_max3_f32 v168, v32, v33, v34
	v_max3_f32 v170, v48, v49, v50
	v_max3_f32 v168, v168, v35, v36
	v_max3_f32 v170, v170, v51, v52
	v_max3_f32 v168, v168, v37, v38
	s_mov_b32 s55, s52
	s_mov_b32 s52, s53
	s_mov_b32 s53, s54
	s_mov_b32 s54, s55
	s_mov_b32 s9, 0
	s_waitcnt lgkmcnt(8)
	v_mfma_f32_32x32x16_bf16 v[16:31], v[180:183], v[96:99], v[16:31]
	v_max3_f32 v170, v170, v53, v54
	v_max3_f32 v168, v168, v39, v40
	v_max3_f32 v170, v170, v55, v56
	v_max3_f32 v168, v168, v41, v42
	v_max3_f32 v170, v170, v57, v58
	v_add_u32_e32 v163, s53, v240
	v_add_u32_e32 v164, s54, v241
	v_mfma_f32_16x16x32_bf16 v[234:237], v[246:249], v[96:99], v[234:237]
	v_max3_f32 v168, v168, v43, v44
	v_max3_f32 v170, v170, v59, v60
	v_max3_f32 v168, v168, v45, v46
	v_max3_f32 v170, v170, v61, v62
	v_max3_f32 v168, v168, v170, v47
	s_waitcnt lgkmcnt(6)
	v_mfma_f32_32x32x16_bf16 v[0:15], v[184:187], v[104:107], v[0:15]
	v_max_f32_e32 v168, v168, v63
	v_cmp_lt_f32_e32 vcc, 0x41000000, v168
	s_cbranch_vccz .Lagqa_nors_8
	v_mov_b32_e32 v170, v168
	s_nop 1
	v_permlane32_swap_b32_e32 v168, v170
	v_max_f32_e32 v168, v168, v170
	v_max_f32_e32 v170, 0, v168
	v_exp_f32_e64 v166, -v170
	v_sub_f32_e32 v218, v218, v170
	v_sub_f32_e32 v219, v219, v170
	v_sub_f32_e32 v220, v220, v170
	v_sub_f32_e32 v221, v221, v170
	v_sub_f32_e32 v222, v222, v170
	v_sub_f32_e32 v223, v223, v170
	v_sub_f32_e32 v224, v224, v170
	v_sub_f32_e32 v225, v225, v170
	v_sub_f32_e32 v226, v226, v170
	v_sub_f32_e32 v227, v227, v170
	v_sub_f32_e32 v228, v228, v170
	v_sub_f32_e32 v229, v229, v170
	v_sub_f32_e32 v230, v230, v170
	v_sub_f32_e32 v231, v231, v170
	v_sub_f32_e32 v232, v232, v170
	v_sub_f32_e32 v233, v233, v170
	v_sub_f32_e32 v32, v32, v170
	v_sub_f32_e32 v33, v33, v170
	v_sub_f32_e32 v34, v34, v170
	v_sub_f32_e32 v35, v35, v170
	v_sub_f32_e32 v36, v36, v170
	v_sub_f32_e32 v37, v37, v170
	v_sub_f32_e32 v38, v38, v170
	v_sub_f32_e32 v39, v39, v170
	v_sub_f32_e32 v40, v40, v170
	v_sub_f32_e32 v41, v41, v170
	v_sub_f32_e32 v42, v42, v170
	v_sub_f32_e32 v43, v43, v170
	v_sub_f32_e32 v44, v44, v170
	v_sub_f32_e32 v45, v45, v170
	v_sub_f32_e32 v46, v46, v170
	v_sub_f32_e32 v47, v47, v170
	v_sub_f32_e32 v48, v48, v170
	v_sub_f32_e32 v49, v49, v170
	v_sub_f32_e32 v50, v50, v170
	v_sub_f32_e32 v51, v51, v170
	v_sub_f32_e32 v52, v52, v170
	v_sub_f32_e32 v53, v53, v170
	v_sub_f32_e32 v54, v54, v170
	v_sub_f32_e32 v55, v55, v170
	v_sub_f32_e32 v56, v56, v170
	v_sub_f32_e32 v57, v57, v170
	v_sub_f32_e32 v58, v58, v170
	v_sub_f32_e32 v59, v59, v170
	v_sub_f32_e32 v60, v60, v170
	v_sub_f32_e32 v61, v61, v170
	v_sub_f32_e32 v62, v62, v170
	v_sub_f32_e32 v63, v63, v170
	s_mov_b32 s9, 1
; #define AT_STEP(SC0, SC1, SN0, SN1, t, DOK, DOV) do { \
;             if (DOK) AT_GLOADK(((t) + 2) * 64); \
;             if (DOV) { AT_GLOADV(((t) + 1) * 64); AT_QK(SN0, SN1, ((t) + 1) & 1); } \
;             AT_SMPV(SC0, SC1, (t) & 1); \
;             if (DOK) AT_WRITEK((t) & 1); \
;             if (DOV) AT_WRITEV(((t) + 1) & 1); \
;             __syncthreads(); } while (0)
; template <bool MLA>
; DI void attn_phase(const int TID, const int BID, LAS unsigned char* lds, const Params& p, bool need_ctx) {
;     ...
;         AT_STEP(sa0, sa1, sb0, sb1, t, false, true);
;         AT_STEP(sb0, sb1, sa0, sa1, t + 1, false, false);
.Lagqa_nors_8:
	v_exp_f32_e32 v32, v32
	ds_read_b64_tr_b16 v[192:193], v162 offset:3072
	ds_read_b64_tr_b16 v[194:195], v162 offset:4608
	s_waitcnt lgkmcnt(6)
	v_mfma_f32_32x32x16_bf16 v[16:31], v[188:191], v[104:107], v[16:31]
	v_exp_f32_e32 v48, v48
	v_exp_f32_e32 v33, v33
	v_exp_f32_e32 v49, v49
	ds_read_b64_tr_b16 v[196:197], v162 offset:3136
	ds_read_b64_tr_b16 v[198:199], v162 offset:4672
	v_mfma_f32_16x16x32_bf16 v[234:237], v[246:249], v[104:107], v[234:237]
	v_exp_f32_e32 v34, v34
	v_exp_f32_e32 v50, v50
	ds_read_b64_tr_b16 v[200:201], v162 offset:9216
	ds_read_b64_tr_b16 v[202:203], v162 offset:10752
	s_waitcnt lgkmcnt(9)
	v_mfma_f32_32x32x16_bf16 v[64:79], v[136:139], v[112:115], v[218:233]
	v_cvt_pk_bf16_f32 v96, v32, v33
	v_cvt_pk_bf16_f32 v104, v48, v49
	v_exp_f32_e32 v35, v35
	v_exp_f32_e32 v51, v51
	ds_read_b128 v[136:139], v243 offset:9280
	ds_read_b64_tr_b16 v[204:205], v162 offset:9280
	ds_read_b64_tr_b16 v[206:207], v162 offset:10816
	s_waitcnt lgkmcnt(11)
	v_mfma_f32_32x32x16_bf16 v[80:95], v[140:143], v[112:115], v[218:233]
	v_exp_f32_e32 v36, v36
	v_exp_f32_e32 v52, v52
	ds_read_b128 v[140:143], v243 offset:13888
	s_waitcnt lgkmcnt(11)
	v_mfma_f32_32x32x16_bf16 v[64:79], v[144:147], v[116:119], v[64:79]
	v_cvt_pk_bf16_f32 v97, v34, v35
	v_cvt_pk_bf16_f32 v105, v50, v51
	v_exp_f32_e32 v37, v37
	v_exp_f32_e32 v53, v53
	ds_read_b128 v[144:147], v243 offset:9312
	s_waitcnt lgkmcnt(11)
	v_mfma_f32_32x32x16_bf16 v[80:95], v[148:151], v[116:119], v[80:95]
	v_exp_f32_e32 v38, v38
	v_exp_f32_e32 v54, v54
	ds_read_b128 v[148:151], v243 offset:13920
	s_waitcnt lgkmcnt(5)
	v_mfma_f32_32x32x16_bf16 v[64:79], v[136:139], v[120:123], v[64:79]
	v_cvt_pk_bf16_f32 v98, v36, v37
	v_cvt_pk_bf16_f32 v106, v52, v53
	v_exp_f32_e32 v39, v39
	s_waitcnt lgkmcnt(2)
	v_mfma_f32_32x32x16_bf16 v[80:95], v[140:143], v[120:123], v[80:95]
	v_exp_f32_e32 v55, v55
	v_exp_f32_e32 v40, v40
	v_exp_f32_e32 v56, v56
	s_waitcnt vmcnt(0)
	ds_write_b128 v164, v[156:159]
	s_waitcnt lgkmcnt(2)
	v_mfma_f32_32x32x16_bf16 v[64:79], v[144:147], v[124:127], v[64:79]
	v_cvt_pk_bf16_f32 v99, v38, v39
	v_cvt_pk_bf16_f32 v107, v54, v55
	v_exp_f32_e32 v41, v41
	s_waitcnt lgkmcnt(1)
	v_mfma_f32_32x32x16_bf16 v[80:95], v[148:151], v[124:127], v[80:95]
	v_exp_f32_e32 v57, v57
	v_exp_f32_e32 v42, v42
	v_exp_f32_e32 v58, v58
	v_mfma_f32_32x32x16_bf16 v[0:15], v[192:195], v[100:103], v[0:15]
	v_exp_f32_e32 v43, v43
	v_exp_f32_e32 v59, v59
	ds_read_b64_tr_b16 v[176:177], v163 offset:0
	ds_read_b64_tr_b16 v[178:179], v163 offset:1536
	v_mfma_f32_32x32x16_bf16 v[16:31], v[196:199], v[100:103], v[16:31]
	v_exp_f32_e32 v44, v44
	v_exp_f32_e32 v60, v60
	v_exp_f32_e32 v45, v45
	ds_read_b64_tr_b16 v[180:181], v163 offset:64
	ds_read_b64_tr_b16 v[182:183], v163 offset:1600
	v_mfma_f32_16x16x32_bf16 v[234:237], v[246:249], v[100:103], v[234:237]
	v_cvt_pk_bf16_f32 v100, v40, v41
	v_cvt_pk_bf16_f32 v101, v42, v43
	v_exp_f32_e32 v61, v61
	v_exp_f32_e32 v46, v46
	ds_read_b64_tr_b16 v[184:185], v163 offset:6144
	ds_read_b64_tr_b16 v[186:187], v163 offset:7680
	v_mfma_f32_32x32x16_bf16 v[0:15], v[200:203], v[108:111], v[0:15]
	v_exp_f32_e32 v62, v62
	v_cvt_pk_bf16_f32 v102, v44, v45
	v_exp_f32_e32 v47, v47
	ds_read_b64_tr_b16 v[188:189], v163 offset:6208
	ds_read_b64_tr_b16 v[190:191], v163 offset:7744
	v_mfma_f32_32x32x16_bf16 v[16:31], v[204:207], v[108:111], v[16:31]
	v_exp_f32_e32 v63, v63
	v_cvt_pk_bf16_f32 v103, v46, v47
	v_mfma_f32_16x16x32_bf16 v[234:237], v[246:249], v[108:111], v[234:237]
	v_cvt_pk_bf16_f32 v108, v56, v57
	v_cvt_pk_bf16_f32 v109, v58, v59
	v_cvt_pk_bf16_f32 v110, v60, v61
	v_cvt_pk_bf16_f32 v111, v62, v63
	s_cmp_lg_u32 s9, 0
	s_cbranch_scc0 .Lagqa_noresc_9
	s_nop 15
	v_mul_f32_e32 v0, v0, v166
	v_mul_f32_e32 v1, v1, v166
	v_mul_f32_e32 v2, v2, v166
	v_mul_f32_e32 v3, v3, v166
	v_mul_f32_e32 v4, v4, v166
	v_mul_f32_e32 v5, v5, v166
	v_mul_f32_e32 v6, v6, v166
	v_mul_f32_e32 v7, v7, v166
	v_mul_f32_e32 v8, v8, v166
	v_mul_f32_e32 v9, v9, v166
	v_mul_f32_e32 v10, v10, v166
	v_mul_f32_e32 v11, v11, v166
	v_mul_f32_e32 v12, v12, v166
	v_mul_f32_e32 v13, v13, v166
	v_mul_f32_e32 v14, v14, v166
	v_mul_f32_e32 v15, v15, v166
	v_mul_f32_e32 v16, v16, v166
	v_mul_f32_e32 v17, v17, v166
	v_mul_f32_e32 v18, v18, v166
	v_mul_f32_e32 v19, v19, v166
	v_mul_f32_e32 v20, v20, v166
	v_mul_f32_e32 v21, v21, v166
	v_mul_f32_e32 v22, v22, v166
	v_mul_f32_e32 v23, v23, v166
	v_mul_f32_e32 v24, v24, v166
	v_mul_f32_e32 v25, v25, v166
	v_mul_f32_e32 v26, v26, v166
	v_mul_f32_e32 v27, v27, v166
	v_mul_f32_e32 v28, v28, v166
	v_mul_f32_e32 v29, v29, v166
	v_mul_f32_e32 v30, v30, v166
	v_mul_f32_e32 v31, v31, v166
	v_add_u32_e32 v170, 64, v175
	ds_bpermute_b32 v173, v170, v166
	v_mul_f32_e32 v234, v234, v166
	s_waitcnt lgkmcnt(0)
	v_mul_f32_e32 v235, v235, v173
